# leading wave half gets its own K-loop copies (all four GEMM loops) with each vmcnt(8) wait moved to the end of the following MFMA segment (one more barrier interval of LDS-DMA latency budget)
# speedup vs baseline: 1.0085x; 1.0005x over previous
; #define PG8_STAGE(bufoff, gbase, voff) do { _Pragma("unroll") for (int _i = 0; _i < 2; ++_i) \
;         __builtin_amdgcn_global_load_lds((const unsigned*)((const char*)(gbase) + (voff)[_i]), (PG8_LAS unsigned*)(lds + (bufoff) + ldsw + _i * 8192), 16, 0, 0); } while (0)
; #define PG8_LDA(dst, b, h) do { _Pragma("unroll") for (int m = 0; m < 4; ++m) _Pragma("unroll") for (int k = 0; k < 2; ++k) dst[m][k] = *(const PG8_LAS bf16x8*)(lds + PG8_SA(b, h) + aoff + m * 2048 + k * 1024); } while (0)
; #define PG8_LDB(dst, b, h) do { _Pragma("unroll") for (int n = 0; n < 2; ++n) _Pragma("unroll") for (int k = 0; k < 2; ++k) dst[n][k] = *(const PG8_LAS bf16x8*)(lds + PG8_SB(b, h) + boff + n * 2048 + k * 1024); } while (0)
; #define PG8_MMA(ai, bj, At, Bt) do { __builtin_amdgcn_s_setprio(1); _Pragma("unroll") for (int m = 0; m < 4; ++m) _Pragma("unroll") for (int n = 0; n < 2; ++n) _Pragma("unroll") for (int k = 0; k < 2; ++k) \
;         acc[ai][bj][m][n] = __builtin_amdgcn_mfma_f32_16x16x32_bf16(Bt[n][k], At[m][k], acc[ai][bj][m][n], 0, 0, 0); __builtin_amdgcn_s_setprio(0); } while (0)
; #define PG8_WAIT_V(n) asm volatile("s_waitcnt vmcnt(" #n ")" ::: "memory")
; #define PG8_WAIT_L(n) asm volatile("s_waitcnt lgkmcnt(" #n ")" ::: "memory")
; #define PG8_BAR __builtin_amdgcn_s_barrier()
; #define PG8_SCHED __builtin_amdgcn_sched_barrier(0)
; template <class Epi, class Sched, bool ALIGN_EPI = false, bool SP2 = false>
; __device__ __forceinline__ void gemm_phase(PG8_LAS unsigned char* lds, const Gemm g, const Sched& S, const Epi& E) {
;     ...
;             PG8_LDB(B0, 0, 0); PG8_LDB(B1, 0, 1); PG8_SCHED; PG8_LDA(At, 0, 0); PG8_STAGE(PG8_SA(1, 1), a1 + hstep, voffA);
;             PG8_WAIT_V(8); PG8_WAIT_L(0); PG8_BAR; PG8_MMA(0, 0, At, B0); PG8_MMA(0, 1, At, B1); PG8_BAR; PG8_SCHED;
;     ...
;         for (int a = 0; a < 2; ++a)
; #pragma unroll
;             for (int b = 0; b < 2; ++b)
; #pragma unroll
;                 for (int m = 0; m < 4; ++m)
; #pragma unroll
;                     for (int n = 0; n < 2; ++n) acc[a][b][m][n] = (f32x4){0.f, 0.f, 0.f, 0.f};
.LBB0_109:
	s_ashr_i32 s17, s16, 31
	s_lshl_b64 s[18:19], s[16:17], 19
	s_add_u32 s18, s30, s18
	s_addc_u32 s19, s31, s19
	s_and_b64 s[42:43], s[4:5], exec
	s_cselect_b32 s17, s19, s45
	s_cselect_b32 s62, s18, s44
	s_ashr_i32 s15, s14, 31
	s_lshl_b64 s[42:43], s[14:15], 19
	s_add_u32 s42, s20, s42
	s_addc_u32 s43, s38, s43
	s_and_b64 s[48:49], s[4:5], exec
	s_cselect_b32 s15, s43, s47
	s_cselect_b32 s63, s42, s46
	s_add_u32 s44, s44, 0x40080
	s_addc_u32 s45, s45, 0
	s_add_u32 s64, s46, 0x100
	v_mov_b32_e32 v0, 0
	s_addc_u32 s65, s47, 0
	s_mov_b32 s66, -2
	v_mov_b32_e32 v1, v0
	v_mov_b32_e32 v2, v0
	v_mov_b32_e32 v3, v0
	v_mov_b32_e32 v8, v0
	v_mov_b32_e32 v9, v0
	v_mov_b32_e32 v10, v0
	v_mov_b32_e32 v11, v0
	v_mov_b32_e32 v16, v0
	v_mov_b32_e32 v17, v0
	v_mov_b32_e32 v18, v0
	v_mov_b32_e32 v19, v0
	v_mov_b32_e32 v24, v0
	v_mov_b32_e32 v25, v0
	v_mov_b32_e32 v26, v0
	v_mov_b32_e32 v27, v0
	v_mov_b32_e32 v32, v0
	v_mov_b32_e32 v33, v0
	v_mov_b32_e32 v34, v0
	v_mov_b32_e32 v35, v0
	v_mov_b32_e32 v40, v0
	v_mov_b32_e32 v41, v0
	v_mov_b32_e32 v42, v0
	v_mov_b32_e32 v43, v0
	v_mov_b32_e32 v48, v0
	v_mov_b32_e32 v49, v0
	v_mov_b32_e32 v50, v0
	v_mov_b32_e32 v51, v0
	v_mov_b32_e32 v56, v0
	v_mov_b32_e32 v57, v0
	v_mov_b32_e32 v58, v0
	v_mov_b32_e32 v59, v0
	v_mov_b32_e32 v4, v0
	v_mov_b32_e32 v5, v0
	v_mov_b32_e32 v6, v0
	v_mov_b32_e32 v7, v0
	v_mov_b32_e32 v12, v0
	v_mov_b32_e32 v13, v0
	v_mov_b32_e32 v14, v0
	v_mov_b32_e32 v15, v0
	v_mov_b32_e32 v20, v0
	v_mov_b32_e32 v21, v0
	v_mov_b32_e32 v22, v0
	v_mov_b32_e32 v23, v0
	v_mov_b32_e32 v28, v0
	v_mov_b32_e32 v29, v0
	v_mov_b32_e32 v30, v0
	v_mov_b32_e32 v31, v0
	v_mov_b32_e32 v36, v0
	v_mov_b32_e32 v37, v0
	v_mov_b32_e32 v38, v0
	v_mov_b32_e32 v39, v0
	v_mov_b32_e32 v44, v0
	v_mov_b32_e32 v45, v0
	v_mov_b32_e32 v46, v0
	v_mov_b32_e32 v47, v0
	v_mov_b32_e32 v52, v0
	v_mov_b32_e32 v53, v0
	v_mov_b32_e32 v54, v0
	v_mov_b32_e32 v55, v0
	v_mov_b32_e32 v60, v0
	v_mov_b32_e32 v61, v0
	v_mov_b32_e32 v62, v0
	v_mov_b32_e32 v63, v0
	v_mov_b32_e32 v64, v0
	v_mov_b32_e32 v65, v0
	v_mov_b32_e32 v66, v0
	v_mov_b32_e32 v67, v0
	v_mov_b32_e32 v72, v0
	v_mov_b32_e32 v73, v0
	v_mov_b32_e32 v74, v0
	v_mov_b32_e32 v75, v0
	v_mov_b32_e32 v82, v0
	v_mov_b32_e32 v83, v0
	v_mov_b32_e32 v84, v0
	v_mov_b32_e32 v85, v0
	v_mov_b32_e32 v90, v0
	v_mov_b32_e32 v91, v0
	v_mov_b32_e32 v92, v0
	v_mov_b32_e32 v93, v0
	v_mov_b32_e32 v98, v0
	v_mov_b32_e32 v99, v0
	v_mov_b32_e32 v100, v0
	v_mov_b32_e32 v101, v0
	v_mov_b32_e32 v106, v0
	v_mov_b32_e32 v107, v0
	v_mov_b32_e32 v108, v0
	v_mov_b32_e32 v109, v0
	v_mov_b32_e32 v114, v0
	v_mov_b32_e32 v115, v0
	v_mov_b32_e32 v116, v0
	v_mov_b32_e32 v117, v0
	v_mov_b32_e32 v122, v0
	v_mov_b32_e32 v123, v0
	v_mov_b32_e32 v124, v0
	v_mov_b32_e32 v125, v0
	v_mov_b32_e32 v68, v0
	v_mov_b32_e32 v69, v0
	v_mov_b32_e32 v70, v0
	v_mov_b32_e32 v71, v0
	v_mov_b32_e32 v76, v0
	v_mov_b32_e32 v77, v0
	v_mov_b32_e32 v78, v0
	v_mov_b32_e32 v79, v0
	v_mov_b32_e32 v86, v0
	v_mov_b32_e32 v87, v0
	v_mov_b32_e32 v88, v0
	v_mov_b32_e32 v89, v0
	v_mov_b32_e32 v94, v0
	v_mov_b32_e32 v95, v0
	v_mov_b32_e32 v96, v0
	v_mov_b32_e32 v97, v0
	v_mov_b32_e32 v102, v0
	v_mov_b32_e32 v103, v0
	v_mov_b32_e32 v104, v0
	v_mov_b32_e32 v105, v0
	v_mov_b32_e32 v110, v0
	v_mov_b32_e32 v111, v0
	v_mov_b32_e32 v112, v0
	v_mov_b32_e32 v113, v0
	v_mov_b32_e32 v118, v0
	v_mov_b32_e32 v119, v0
	v_mov_b32_e32 v120, v0
	v_mov_b32_e32 v121, v0
	v_mov_b32_e32 v126, v0
	v_mov_b32_e32 v127, v0
	v_mov_b32_e32 v128, v0
	v_mov_b32_e32 v129, v0
	v_readfirstlane_b32 s100, v202
	s_nop 3
	s_lshr_b32 s100, s100, 8
	s_cmp_eq_u32 s100, 0
	s_cbranch_scc0 .LBB0_110
.Lffn_A:
	s_add_u32 s46, s44, 0xfffc0080
	s_addc_u32 s47, s45, -1
	s_add_i32 s67, 0, 0x10000
	s_cmp_eq_u32 s66, 12
	s_cselect_b32 s49, s17, s47
	s_cselect_b32 s48, s62, s46
	v_add_u32_e32 v145, s67, v143
	s_cselect_b32 s47, s15, s65
	s_cselect_b32 s46, s63, s64
	s_add_i32 s70, 0, 0x14000
	ds_read_b128 v[146:149], v145
	ds_read_b128 v[150:153], v145 offset:1024
	ds_read_b128 v[154:157], v145 offset:2048
	ds_read_b128 v[158:161], v145 offset:3072
	v_add_u32_e32 v145, s70, v143
	ds_read_b128 v[176:179], v145
	ds_read_b128 v[180:183], v145 offset:1024
	ds_read_b128 v[184:187], v145 offset:2048
	ds_read_b128 v[188:191], v145 offset:3072
	v_lshl_add_u64 v[200:201], s[44:45], 0, v[138:139]
	s_add_i32 m0, s50, 0xc000
	ds_read_b128 v[192:195], v144
	ds_read_b128 v[196:199], v144 offset:1024
	ds_read_b128 v[208:211], v144 offset:2048
	ds_read_b128 v[212:215], v144 offset:3072
	ds_read_b128 v[216:219], v144 offset:4096
	ds_read_b128 v[220:223], v144 offset:5120
	ds_read_b128 v[224:227], v144 offset:6144
	ds_read_b128 v[228:231], v144 offset:7168
	global_load_lds_dwordx4 v[200:201], off
	v_lshl_add_u64 v[200:201], s[44:45], 0, v[140:141]
	s_add_i32 m0, s50, 0xe000
	s_nop 0
	global_load_lds_dwordx4 v[200:201], off
	s_waitcnt lgkmcnt(0)
	s_setprio 1
	s_barrier
; #define PG8_STAGE(bufoff, gbase, voff) do { _Pragma("unroll") for (int _i = 0; _i < 2; ++_i) \
;         __builtin_amdgcn_global_load_lds((const unsigned*)((const char*)(gbase) + (voff)[_i]), (PG8_LAS unsigned*)(lds + (bufoff) + ldsw + _i * 8192), 16, 0, 0); } while (0)
; #define PG8_LDA(dst, b, h) do { _Pragma("unroll") for (int m = 0; m < 4; ++m) _Pragma("unroll") for (int k = 0; k < 2; ++k) dst[m][k] = *(const PG8_LAS bf16x8*)(lds + PG8_SA(b, h) + aoff + m * 2048 + k * 1024); } while (0)
; #define PG8_MMA(ai, bj, At, Bt) do { __builtin_amdgcn_s_setprio(1); _Pragma("unroll") for (int m = 0; m < 4; ++m) _Pragma("unroll") for (int n = 0; n < 2; ++n) _Pragma("unroll") for (int k = 0; k < 2; ++k) \
;         acc[ai][bj][m][n] = __builtin_amdgcn_mfma_f32_16x16x32_bf16(Bt[n][k], At[m][k], acc[ai][bj][m][n], 0, 0, 0); __builtin_amdgcn_s_setprio(0); } while (0)
; #define PG8_WAIT_V(n) asm volatile("s_waitcnt vmcnt(" #n ")" ::: "memory")
; #define PG8_WAIT_L(n) asm volatile("s_waitcnt lgkmcnt(" #n ")" ::: "memory")
; #define PG8_BAR __builtin_amdgcn_s_barrier()
; #define PG8_SCHED __builtin_amdgcn_sched_barrier(0)
; template <class Epi, class Sched, bool ALIGN_EPI = false, bool SP2 = false>
; __device__ __forceinline__ void gemm_phase(PG8_LAS unsigned char* lds, const Gemm g, const Sched& S, const Epi& E) {
;     ...
;             PG8_WAIT_V(8); PG8_WAIT_L(0); PG8_BAR; PG8_MMA(0, 0, At, B0); PG8_MMA(0, 1, At, B1); PG8_BAR; PG8_SCHED;
;             PG8_LDA(At, 0, 1); PG8_STAGE(PG8_SB(0, 0), b2, voffB); PG8_STAGE(PG8_SB(0, 1), b2 + hstep, voffB); PG8_STAGE(PG8_SA(0, 0), a2, voffA);
;             PG8_WAIT_V(8); PG8_WAIT_L(0); PG8_BAR; PG8_MMA(1, 0, At, B0); PG8_MMA(1, 1, At, B1); PG8_BAR; PG8_SCHED;
	v_mfma_f32_16x16x32_bf16 v[126:129], v[146:149], v[192:195], v[126:129]
	v_mfma_f32_16x16x32_bf16 v[118:121], v[154:157], v[192:195], v[118:121]
	v_mfma_f32_16x16x32_bf16 v[110:113], v[146:149], v[208:211], v[110:113]
	v_mfma_f32_16x16x32_bf16 v[102:105], v[154:157], v[208:211], v[102:105]
	v_mfma_f32_16x16x32_bf16 v[94:97], v[146:149], v[216:219], v[94:97]
	v_mfma_f32_16x16x32_bf16 v[86:89], v[154:157], v[216:219], v[86:89]
	v_mfma_f32_16x16x32_bf16 v[76:79], v[146:149], v[224:227], v[76:79]
	v_mfma_f32_16x16x32_bf16 v[68:71], v[154:157], v[224:227], v[68:71]
	v_mfma_f32_16x16x32_bf16 v[126:129], v[150:153], v[196:199], v[126:129]
	v_mfma_f32_16x16x32_bf16 v[118:121], v[158:161], v[196:199], v[118:121]
	v_mfma_f32_16x16x32_bf16 v[110:113], v[150:153], v[212:215], v[110:113]
	v_mfma_f32_16x16x32_bf16 v[102:105], v[158:161], v[212:215], v[102:105]
	v_mfma_f32_16x16x32_bf16 v[94:97], v[150:153], v[220:223], v[94:97]
	v_mfma_f32_16x16x32_bf16 v[86:89], v[158:161], v[220:223], v[86:89]
	v_mfma_f32_16x16x32_bf16 v[76:79], v[150:153], v[228:231], v[76:79]
	v_mfma_f32_16x16x32_bf16 v[68:71], v[158:161], v[228:231], v[68:71]
	v_mfma_f32_16x16x32_bf16 v[122:125], v[176:179], v[192:195], v[122:125]
	v_mfma_f32_16x16x32_bf16 v[114:117], v[184:187], v[192:195], v[114:117]
	v_mfma_f32_16x16x32_bf16 v[106:109], v[176:179], v[208:211], v[106:109]
	v_mfma_f32_16x16x32_bf16 v[98:101], v[184:187], v[208:211], v[98:101]
	v_mfma_f32_16x16x32_bf16 v[90:93], v[176:179], v[216:219], v[90:93]
	v_mfma_f32_16x16x32_bf16 v[82:85], v[184:187], v[216:219], v[82:85]
	v_mfma_f32_16x16x32_bf16 v[72:75], v[176:179], v[224:227], v[72:75]
	v_mfma_f32_16x16x32_bf16 v[64:67], v[184:187], v[224:227], v[64:67]
	v_mfma_f32_16x16x32_bf16 v[122:125], v[180:183], v[196:199], v[122:125]
	v_mfma_f32_16x16x32_bf16 v[114:117], v[188:191], v[196:199], v[114:117]
	v_mfma_f32_16x16x32_bf16 v[106:109], v[180:183], v[212:215], v[106:109]
	v_mfma_f32_16x16x32_bf16 v[98:101], v[188:191], v[212:215], v[98:101]
	v_mfma_f32_16x16x32_bf16 v[90:93], v[180:183], v[220:223], v[90:93]
	v_mfma_f32_16x16x32_bf16 v[82:85], v[188:191], v[220:223], v[82:85]
	v_mfma_f32_16x16x32_bf16 v[72:75], v[180:183], v[228:231], v[72:75]
	v_mfma_f32_16x16x32_bf16 v[64:67], v[188:191], v[228:231], v[64:67]
	s_waitcnt vmcnt(8)
	s_setprio 0
	s_barrier
	s_add_i32 s67, s67, s39
	v_lshl_add_u64 v[200:201], s[46:47], 0, v[134:135]
	s_mov_b32 m0, s67
	ds_read_b128 v[192:195], v144 offset:16384
	ds_read_b128 v[196:199], v144 offset:17408
	ds_read_b128 v[208:211], v144 offset:18432
	ds_read_b128 v[212:215], v144 offset:19456
	ds_read_b128 v[216:219], v144 offset:20480
	ds_read_b128 v[220:223], v144 offset:21504
	ds_read_b128 v[224:227], v144 offset:22528
	ds_read_b128 v[228:231], v144 offset:23552
	global_load_lds_dwordx4 v[200:201], off
	s_add_i32 m0, s67, 0x2000
	s_add_u32 s68, s46, 0x40000
	v_lshl_add_u64 v[232:233], s[46:47], 0, v[130:131]
	s_addc_u32 s69, s47, 0
	s_add_i32 s67, s70, s39
	global_load_lds_dwordx4 v[232:233], off
	v_lshl_add_u64 v[234:235], s[68:69], 0, v[134:135]
	s_mov_b32 m0, s67
	v_lshl_add_u64 v[236:237], s[48:49], 0, v[132:133]
	global_load_lds_dwordx4 v[234:235], off
	v_lshl_add_u64 v[234:235], s[68:69], 0, v[130:131]
	s_add_i32 m0, s67, 0x2000
	s_nop 0
	global_load_lds_dwordx4 v[234:235], off
	v_lshl_add_u64 v[234:235], s[48:49], 0, v[136:137]
	s_mov_b32 m0, s50
	s_nop 0
	global_load_lds_dwordx4 v[234:235], off
	s_mov_b32 m0, s51
	s_nop 0
	global_load_lds_dwordx4 v[236:237], off
	s_waitcnt lgkmcnt(0)
	s_setprio 1
	s_barrier
	v_mfma_f32_16x16x32_bf16 v[60:63], v[146:149], v[192:195], v[60:63]
	v_mfma_f32_16x16x32_bf16 v[52:55], v[154:157], v[192:195], v[52:55]
	v_mfma_f32_16x16x32_bf16 v[44:47], v[146:149], v[208:211], v[44:47]
	v_mfma_f32_16x16x32_bf16 v[36:39], v[154:157], v[208:211], v[36:39]
	v_mfma_f32_16x16x32_bf16 v[28:31], v[146:149], v[216:219], v[28:31]
	v_mfma_f32_16x16x32_bf16 v[20:23], v[154:157], v[216:219], v[20:23]
	v_mfma_f32_16x16x32_bf16 v[12:15], v[146:149], v[224:227], v[12:15]
	v_mfma_f32_16x16x32_bf16 v[4:7], v[154:157], v[224:227], v[4:7]
	v_mfma_f32_16x16x32_bf16 v[60:63], v[150:153], v[196:199], v[60:63]
	v_mfma_f32_16x16x32_bf16 v[52:55], v[158:161], v[196:199], v[52:55]
	v_mfma_f32_16x16x32_bf16 v[44:47], v[150:153], v[212:215], v[44:47]
	v_mfma_f32_16x16x32_bf16 v[36:39], v[158:161], v[212:215], v[36:39]
	v_mfma_f32_16x16x32_bf16 v[28:31], v[150:153], v[220:223], v[28:31]
	v_mfma_f32_16x16x32_bf16 v[20:23], v[158:161], v[220:223], v[20:23]
	v_mfma_f32_16x16x32_bf16 v[12:15], v[150:153], v[228:231], v[12:15]
	v_mfma_f32_16x16x32_bf16 v[4:7], v[158:161], v[228:231], v[4:7]
	v_mfma_f32_16x16x32_bf16 v[56:59], v[176:179], v[192:195], v[56:59]
	v_mfma_f32_16x16x32_bf16 v[48:51], v[184:187], v[192:195], v[48:51]
	v_mfma_f32_16x16x32_bf16 v[40:43], v[176:179], v[208:211], v[40:43]
	v_mfma_f32_16x16x32_bf16 v[32:35], v[184:187], v[208:211], v[32:35]
	v_mfma_f32_16x16x32_bf16 v[24:27], v[176:179], v[216:219], v[24:27]
	v_mfma_f32_16x16x32_bf16 v[16:19], v[184:187], v[216:219], v[16:19]
	v_mfma_f32_16x16x32_bf16 v[8:11], v[176:179], v[224:227], v[8:11]
	v_mfma_f32_16x16x32_bf16 v[0:3], v[184:187], v[224:227], v[0:3]
	v_mfma_f32_16x16x32_bf16 v[56:59], v[180:183], v[196:199], v[56:59]
	v_mfma_f32_16x16x32_bf16 v[48:51], v[188:191], v[196:199], v[48:51]
	v_mfma_f32_16x16x32_bf16 v[40:43], v[180:183], v[212:215], v[40:43]
	v_mfma_f32_16x16x32_bf16 v[32:35], v[188:191], v[212:215], v[32:35]
	v_mfma_f32_16x16x32_bf16 v[24:27], v[180:183], v[220:223], v[24:27]
	v_mfma_f32_16x16x32_bf16 v[16:19], v[188:191], v[220:223], v[16:19]
	v_mfma_f32_16x16x32_bf16 v[8:11], v[180:183], v[228:231], v[8:11]
	v_mfma_f32_16x16x32_bf16 v[0:3], v[188:191], v[228:231], v[0:3]
	s_waitcnt vmcnt(8)
	s_setprio 0
	s_barrier
; #define PG8_STAGE(bufoff, gbase, voff) do { _Pragma("unroll") for (int _i = 0; _i < 2; ++_i) \
;         __builtin_amdgcn_global_load_lds((const unsigned*)((const char*)(gbase) + (voff)[_i]), (PG8_LAS unsigned*)(lds + (bufoff) + ldsw + _i * 8192), 16, 0, 0); } while (0)
; #define PG8_LDA(dst, b, h) do { _Pragma("unroll") for (int m = 0; m < 4; ++m) _Pragma("unroll") for (int k = 0; k < 2; ++k) dst[m][k] = *(const PG8_LAS bf16x8*)(lds + PG8_SA(b, h) + aoff + m * 2048 + k * 1024); } while (0)
; #define PG8_LDB(dst, b, h) do { _Pragma("unroll") for (int n = 0; n < 2; ++n) _Pragma("unroll") for (int k = 0; k < 2; ++k) dst[n][k] = *(const PG8_LAS bf16x8*)(lds + PG8_SB(b, h) + boff + n * 2048 + k * 1024); } while (0)
; #define PG8_MMA(ai, bj, At, Bt) do { __builtin_amdgcn_s_setprio(1); _Pragma("unroll") for (int m = 0; m < 4; ++m) _Pragma("unroll") for (int n = 0; n < 2; ++n) _Pragma("unroll") for (int k = 0; k < 2; ++k) \
;         acc[ai][bj][m][n] = __builtin_amdgcn_mfma_f32_16x16x32_bf16(Bt[n][k], At[m][k], acc[ai][bj][m][n], 0, 0, 0); __builtin_amdgcn_s_setprio(0); } while (0)
; #define PG8_WAIT_V(n) asm volatile("s_waitcnt vmcnt(" #n ")" ::: "memory")
; #define PG8_WAIT_L(n) asm volatile("s_waitcnt lgkmcnt(" #n ")" ::: "memory")
; #define PG8_BAR __builtin_amdgcn_s_barrier()
; #define PG8_SCHED __builtin_amdgcn_sched_barrier(0)
; template <class Epi, class Sched, bool ALIGN_EPI = false, bool SP2 = false>
; __device__ __forceinline__ void gemm_phase(PG8_LAS unsigned char* lds, const Gemm g, const Sched& S, const Epi& E) {
;     ...
;             PG8_LDB(B0, 1, 0); PG8_LDB(B1, 1, 1); PG8_SCHED; PG8_LDA(At, 1, 0); PG8_STAGE(PG8_SA(0, 1), a2 + hstep, voffA);
;             PG8_WAIT_V(8); PG8_WAIT_L(0); PG8_BAR; PG8_MMA(0, 0, At, B0); PG8_MMA(0, 1, At, B1); PG8_BAR; PG8_SCHED;
	s_add_i32 s67, 0, 0x18000
	v_add_u32_e32 v145, s67, v143
	s_add_i32 s68, 0, 0x1c000
	ds_read_b128 v[146:149], v145
	ds_read_b128 v[150:153], v145 offset:1024
	ds_read_b128 v[154:157], v145 offset:2048
	ds_read_b128 v[158:161], v145 offset:3072
	v_add_u32_e32 v145, s68, v143
	ds_read_b128 v[176:179], v145
	ds_read_b128 v[180:183], v145 offset:1024
	ds_read_b128 v[184:187], v145 offset:2048
	ds_read_b128 v[188:191], v145 offset:3072
	s_add_u32 s48, s48, 0x40000
	s_addc_u32 s49, s49, 0
	s_mov_b32 m0, s52
	v_lshl_add_u64 v[238:239], s[48:49], 0, v[136:137]
	ds_read_b128 v[192:195], v144 offset:32768
	ds_read_b128 v[196:199], v144 offset:33792
	ds_read_b128 v[208:211], v144 offset:34816
	ds_read_b128 v[212:215], v144 offset:35840
	ds_read_b128 v[216:219], v144 offset:36864
	ds_read_b128 v[220:223], v144 offset:37888
	ds_read_b128 v[224:227], v144 offset:38912
	ds_read_b128 v[228:231], v144 offset:39936
	global_load_lds_dwordx4 v[238:239], off
	v_lshl_add_u64 v[238:239], s[48:49], 0, v[132:133]
	s_mov_b32 m0, s53
	s_nop 0
	global_load_lds_dwordx4 v[238:239], off
	s_waitcnt lgkmcnt(0)
	s_setprio 1
	s_barrier
	v_mfma_f32_16x16x32_bf16 v[126:129], v[146:149], v[192:195], v[126:129]
	v_mfma_f32_16x16x32_bf16 v[118:121], v[154:157], v[192:195], v[118:121]
	v_mfma_f32_16x16x32_bf16 v[110:113], v[146:149], v[208:211], v[110:113]
	v_mfma_f32_16x16x32_bf16 v[102:105], v[154:157], v[208:211], v[102:105]
	v_mfma_f32_16x16x32_bf16 v[94:97], v[146:149], v[216:219], v[94:97]
	v_mfma_f32_16x16x32_bf16 v[86:89], v[154:157], v[216:219], v[86:89]
	v_mfma_f32_16x16x32_bf16 v[76:79], v[146:149], v[224:227], v[76:79]
	v_mfma_f32_16x16x32_bf16 v[68:71], v[154:157], v[224:227], v[68:71]
	v_mfma_f32_16x16x32_bf16 v[126:129], v[150:153], v[196:199], v[126:129]
	v_mfma_f32_16x16x32_bf16 v[118:121], v[158:161], v[196:199], v[118:121]
	v_mfma_f32_16x16x32_bf16 v[110:113], v[150:153], v[212:215], v[110:113]
	v_mfma_f32_16x16x32_bf16 v[102:105], v[158:161], v[212:215], v[102:105]
	v_mfma_f32_16x16x32_bf16 v[94:97], v[150:153], v[220:223], v[94:97]
	v_mfma_f32_16x16x32_bf16 v[86:89], v[158:161], v[220:223], v[86:89]
	v_mfma_f32_16x16x32_bf16 v[76:79], v[150:153], v[228:231], v[76:79]
	v_mfma_f32_16x16x32_bf16 v[68:71], v[158:161], v[228:231], v[68:71]
	v_mfma_f32_16x16x32_bf16 v[122:125], v[176:179], v[192:195], v[122:125]
	v_mfma_f32_16x16x32_bf16 v[114:117], v[184:187], v[192:195], v[114:117]
	v_mfma_f32_16x16x32_bf16 v[106:109], v[176:179], v[208:211], v[106:109]
	v_mfma_f32_16x16x32_bf16 v[98:101], v[184:187], v[208:211], v[98:101]
	v_mfma_f32_16x16x32_bf16 v[90:93], v[176:179], v[216:219], v[90:93]
	v_mfma_f32_16x16x32_bf16 v[82:85], v[184:187], v[216:219], v[82:85]
	v_mfma_f32_16x16x32_bf16 v[72:75], v[176:179], v[224:227], v[72:75]
	v_mfma_f32_16x16x32_bf16 v[64:67], v[184:187], v[224:227], v[64:67]
	v_mfma_f32_16x16x32_bf16 v[122:125], v[180:183], v[196:199], v[122:125]
	v_mfma_f32_16x16x32_bf16 v[114:117], v[188:191], v[196:199], v[114:117]
	v_mfma_f32_16x16x32_bf16 v[106:109], v[180:183], v[212:215], v[106:109]
	v_mfma_f32_16x16x32_bf16 v[98:101], v[188:191], v[212:215], v[98:101]
	v_mfma_f32_16x16x32_bf16 v[90:93], v[180:183], v[220:223], v[90:93]
	v_mfma_f32_16x16x32_bf16 v[82:85], v[188:191], v[220:223], v[82:85]
	v_mfma_f32_16x16x32_bf16 v[72:75], v[180:183], v[228:231], v[72:75]
	v_mfma_f32_16x16x32_bf16 v[64:67], v[188:191], v[228:231], v[64:67]
	s_waitcnt vmcnt(8)
	s_setprio 0
	s_barrier
; #define PG8_STAGE(bufoff, gbase, voff) do { _Pragma("unroll") for (int _i = 0; _i < 2; ++_i) \
;         __builtin_amdgcn_global_load_lds((const unsigned*)((const char*)(gbase) + (voff)[_i]), (PG8_LAS unsigned*)(lds + (bufoff) + ldsw + _i * 8192), 16, 0, 0); } while (0)
; #define PG8_LDA(dst, b, h) do { _Pragma("unroll") for (int m = 0; m < 4; ++m) _Pragma("unroll") for (int k = 0; k < 2; ++k) dst[m][k] = *(const PG8_LAS bf16x8*)(lds + PG8_SA(b, h) + aoff + m * 2048 + k * 1024); } while (0)
; #define PG8_MMA(ai, bj, At, Bt) do { __builtin_amdgcn_s_setprio(1); _Pragma("unroll") for (int m = 0; m < 4; ++m) _Pragma("unroll") for (int n = 0; n < 2; ++n) _Pragma("unroll") for (int k = 0; k < 2; ++k) \
;         acc[ai][bj][m][n] = __builtin_amdgcn_mfma_f32_16x16x32_bf16(Bt[n][k], At[m][k], acc[ai][bj][m][n], 0, 0, 0); __builtin_amdgcn_s_setprio(0); } while (0)
; #define PG8_WAIT_V(n) asm volatile("s_waitcnt vmcnt(" #n ")" ::: "memory")
; #define PG8_WAIT_L(n) asm volatile("s_waitcnt lgkmcnt(" #n ")" ::: "memory")
; #define PG8_BAR __builtin_amdgcn_s_barrier()
; #define PG8_SCHED __builtin_amdgcn_sched_barrier(0)
; template <class Epi, class Sched, bool ALIGN_EPI = false, bool SP2 = false>
; __device__ __forceinline__ void gemm_phase(PG8_LAS unsigned char* lds, const Gemm g, const Sched& S, const Epi& E) {
;     ...
;         for (int t = 0; t < nt; t += 2) {
;     ...
;             PG8_LDA(At, 1, 1); PG8_STAGE(PG8_SB(1, 0), b3, voffB); PG8_STAGE(PG8_SB(1, 1), b3 + hstep, voffB); PG8_STAGE(PG8_SA(1, 0), a3, voffA);
;             PG8_WAIT_V(8); PG8_WAIT_L(0); PG8_BAR; PG8_MMA(1, 0, At, B0); PG8_MMA(1, 1, At, B1); PG8_BAR; PG8_SCHED;
	s_add_i32 s48, s67, s39
	v_lshl_add_u64 v[200:201], v[200:201], 0, s[40:41]
	s_mov_b32 m0, s48
	ds_read_b128 v[192:195], v144 offset:49152
	ds_read_b128 v[196:199], v144 offset:50176
	ds_read_b128 v[208:211], v144 offset:51200
	ds_read_b128 v[212:215], v144 offset:52224
	ds_read_b128 v[216:219], v144 offset:53248
	ds_read_b128 v[220:223], v144 offset:54272
	ds_read_b128 v[224:227], v144 offset:55296
	ds_read_b128 v[228:231], v144 offset:56320
	global_load_lds_dwordx4 v[200:201], off
	s_add_i32 m0, s48, 0x2000
	s_add_u32 s46, s46, 0x40080
	v_lshl_add_u64 v[200:201], v[232:233], 0, s[40:41]
	s_addc_u32 s47, s47, 0
	s_add_i32 s48, s68, s39
	global_load_lds_dwordx4 v[200:201], off
	v_lshl_add_u64 v[200:201], s[46:47], 0, v[134:135]
	s_mov_b32 m0, s48
	s_nop 0
	global_load_lds_dwordx4 v[200:201], off
	v_lshl_add_u64 v[200:201], s[46:47], 0, v[130:131]
	s_add_i32 m0, s48, 0x2000
	s_nop 0
	global_load_lds_dwordx4 v[200:201], off
	v_lshl_add_u64 v[200:201], v[234:235], 0, s[40:41]
	s_mov_b32 m0, s56
	s_nop 0
	global_load_lds_dwordx4 v[200:201], off
	v_lshl_add_u64 v[200:201], v[236:237], 0, s[40:41]
	s_mov_b32 m0, s57
	s_nop 0
	global_load_lds_dwordx4 v[200:201], off
	s_waitcnt lgkmcnt(0)
	s_setprio 1
	s_barrier
	v_mfma_f32_16x16x32_bf16 v[60:63], v[146:149], v[192:195], v[60:63]
	v_mfma_f32_16x16x32_bf16 v[52:55], v[154:157], v[192:195], v[52:55]
	v_mfma_f32_16x16x32_bf16 v[44:47], v[146:149], v[208:211], v[44:47]
	v_mfma_f32_16x16x32_bf16 v[36:39], v[154:157], v[208:211], v[36:39]
	v_mfma_f32_16x16x32_bf16 v[28:31], v[146:149], v[216:219], v[28:31]
	v_mfma_f32_16x16x32_bf16 v[20:23], v[154:157], v[216:219], v[20:23]
	v_mfma_f32_16x16x32_bf16 v[12:15], v[146:149], v[224:227], v[12:15]
	v_mfma_f32_16x16x32_bf16 v[4:7], v[154:157], v[224:227], v[4:7]
	v_mfma_f32_16x16x32_bf16 v[60:63], v[150:153], v[196:199], v[60:63]
	v_mfma_f32_16x16x32_bf16 v[52:55], v[158:161], v[196:199], v[52:55]
	v_mfma_f32_16x16x32_bf16 v[44:47], v[150:153], v[212:215], v[44:47]
	v_mfma_f32_16x16x32_bf16 v[36:39], v[158:161], v[212:215], v[36:39]
	v_mfma_f32_16x16x32_bf16 v[28:31], v[150:153], v[220:223], v[28:31]
	v_mfma_f32_16x16x32_bf16 v[20:23], v[158:161], v[220:223], v[20:23]
	v_mfma_f32_16x16x32_bf16 v[12:15], v[150:153], v[228:231], v[12:15]
	v_mfma_f32_16x16x32_bf16 v[4:7], v[158:161], v[228:231], v[4:7]
	v_mfma_f32_16x16x32_bf16 v[56:59], v[176:179], v[192:195], v[56:59]
	v_mfma_f32_16x16x32_bf16 v[48:51], v[184:187], v[192:195], v[48:51]
	v_mfma_f32_16x16x32_bf16 v[40:43], v[176:179], v[208:211], v[40:43]
	v_mfma_f32_16x16x32_bf16 v[32:35], v[184:187], v[208:211], v[32:35]
	v_mfma_f32_16x16x32_bf16 v[24:27], v[176:179], v[216:219], v[24:27]
	v_mfma_f32_16x16x32_bf16 v[16:19], v[184:187], v[216:219], v[16:19]
	v_mfma_f32_16x16x32_bf16 v[8:11], v[176:179], v[224:227], v[8:11]
	v_mfma_f32_16x16x32_bf16 v[0:3], v[184:187], v[224:227], v[0:3]
	v_mfma_f32_16x16x32_bf16 v[56:59], v[180:183], v[196:199], v[56:59]
	v_mfma_f32_16x16x32_bf16 v[48:51], v[188:191], v[196:199], v[48:51]
	v_mfma_f32_16x16x32_bf16 v[40:43], v[180:183], v[212:215], v[40:43]
	v_mfma_f32_16x16x32_bf16 v[32:35], v[188:191], v[212:215], v[32:35]
	v_mfma_f32_16x16x32_bf16 v[24:27], v[180:183], v[220:223], v[24:27]
	v_mfma_f32_16x16x32_bf16 v[16:19], v[188:191], v[220:223], v[16:19]
	v_mfma_f32_16x16x32_bf16 v[8:11], v[180:183], v[228:231], v[8:11]
	v_mfma_f32_16x16x32_bf16 v[0:3], v[188:191], v[228:231], v[0:3]
	s_waitcnt vmcnt(8)
	s_setprio 0
	s_barrier
	s_add_i32 s66, s66, 2
	s_add_u32 s44, s44, 0x100
	s_addc_u32 s45, s45, 0
	s_add_u32 s64, s64, 0x100
	s_addc_u32 s65, s65, 0
	s_cmp_gt_u32 s66, 13
	s_cbranch_scc0 .Lffn_A
	s_branch .Lffn_done

; #define PG8_STAGE(bufoff, gbase, voff) do { _Pragma("unroll") for (int _i = 0; _i < 2; ++_i) \
;         __builtin_amdgcn_global_load_lds((const unsigned*)((const char*)(gbase) + (voff)[_i]), (PG8_LAS unsigned*)(lds + (bufoff) + ldsw + _i * 8192), 16, 0, 0); } while (0)
; #define PG8_LDA(dst, b, h) do { _Pragma("unroll") for (int m = 0; m < 4; ++m) _Pragma("unroll") for (int k = 0; k < 2; ++k) dst[m][k] = *(const PG8_LAS bf16x8*)(lds + PG8_SA(b, h) + aoff + m * 2048 + k * 1024); } while (0)
; #define PG8_LDB(dst, b, h) do { _Pragma("unroll") for (int n = 0; n < 2; ++n) _Pragma("unroll") for (int k = 0; k < 2; ++k) dst[n][k] = *(const PG8_LAS bf16x8*)(lds + PG8_SB(b, h) + boff + n * 2048 + k * 1024); } while (0)
; #define PG8_MMA(ai, bj, At, Bt) do { __builtin_amdgcn_s_setprio(1); _Pragma("unroll") for (int m = 0; m < 4; ++m) _Pragma("unroll") for (int n = 0; n < 2; ++n) _Pragma("unroll") for (int k = 0; k < 2; ++k) \
;         acc[ai][bj][m][n] = __builtin_amdgcn_mfma_f32_16x16x32_bf16(Bt[n][k], At[m][k], acc[ai][bj][m][n], 0, 0, 0); __builtin_amdgcn_s_setprio(0); } while (0)
; #define PG8_WAIT_V(n) asm volatile("s_waitcnt vmcnt(" #n ")" ::: "memory")
; #define PG8_WAIT_L(n) asm volatile("s_waitcnt lgkmcnt(" #n ")" ::: "memory")
; #define PG8_BAR __builtin_amdgcn_s_barrier()
; #define PG8_SCHED __builtin_amdgcn_sched_barrier(0)
; template <class Epi, class Sched, bool ALIGN_EPI = false, bool SP2 = false>
; __device__ __forceinline__ void gemm_phase(PG8_LAS unsigned char* lds, const Gemm g, const Sched& S, const Epi& E) {
;     ...
;             PG8_LDB(B0, 0, 0); PG8_LDB(B1, 0, 1); PG8_SCHED; PG8_LDA(At, 0, 0); PG8_STAGE(PG8_SA(1, 1), a1 + hstep, voffA);
;             PG8_WAIT_V(8); PG8_WAIT_L(0); PG8_BAR; PG8_MMA(0, 0, At, B0); PG8_MMA(0, 1, At, B1); PG8_BAR; PG8_SCHED;
;     ...
; #pragma unroll
;         for (int a = 0; a < 2; ++a)
; #pragma unroll
;             for (int b = 0; b < 2; ++b)
; #pragma unroll
;                 for (int m = 0; m < 4; ++m)
; #pragma unroll
;                     for (int n = 0; n < 2; ++n) acc[a][b][m][n] = (f32x4){0.f, 0.f, 0.f, 0.f};
;         cur = nxt; cA = nA; cB = nB; ++ui;
.LBB0_128:
	s_ashr_i32 s19, s18, 31
	s_lshl_b64 s[42:43], s[18:19], 19
	s_add_u32 s42, s30, s42
	s_addc_u32 s43, s31, s43
	s_and_b64 s[44:45], s[4:5], exec
	s_cselect_b32 s19, s43, s47
	s_cselect_b32 s64, s42, s46
	s_ashr_i32 s17, s16, 31
	s_lshl_b64 s[44:45], s[16:17], 19
	s_add_u32 s44, s38, s44
	s_addc_u32 s45, s39, s45
	s_and_b64 s[50:51], s[4:5], exec
	s_cselect_b32 s17, s45, s49
	s_cselect_b32 s65, s44, s48
	s_add_u32 s46, s46, 0x40080
	s_addc_u32 s47, s47, 0
	s_add_u32 s66, s48, 0x100
	v_mov_b32_e32 v0, 0
	s_addc_u32 s67, s49, 0
	s_mov_b32 s68, -2
	v_mov_b32_e32 v1, v0
	v_mov_b32_e32 v2, v0
	v_mov_b32_e32 v3, v0
	v_mov_b32_e32 v4, v0
	v_mov_b32_e32 v5, v0
	v_mov_b32_e32 v6, v0
	v_mov_b32_e32 v7, v0
	v_mov_b32_e32 v12, v0
	v_mov_b32_e32 v13, v0
	v_mov_b32_e32 v14, v0
	v_mov_b32_e32 v15, v0
	v_mov_b32_e32 v20, v0
	v_mov_b32_e32 v21, v0
	v_mov_b32_e32 v22, v0
	v_mov_b32_e32 v23, v0
	v_mov_b32_e32 v28, v0
	v_mov_b32_e32 v29, v0
	v_mov_b32_e32 v30, v0
	v_mov_b32_e32 v31, v0
	v_mov_b32_e32 v36, v0
	v_mov_b32_e32 v37, v0
	v_mov_b32_e32 v38, v0
	v_mov_b32_e32 v39, v0
	v_mov_b32_e32 v44, v0
	v_mov_b32_e32 v45, v0
	v_mov_b32_e32 v46, v0
	v_mov_b32_e32 v47, v0
	v_mov_b32_e32 v52, v0
	v_mov_b32_e32 v53, v0
	v_mov_b32_e32 v54, v0
	v_mov_b32_e32 v55, v0
	v_mov_b32_e32 v8, v0
	v_mov_b32_e32 v9, v0
	v_mov_b32_e32 v10, v0
	v_mov_b32_e32 v11, v0
	v_mov_b32_e32 v16, v0
	v_mov_b32_e32 v17, v0
	v_mov_b32_e32 v18, v0
	v_mov_b32_e32 v19, v0
	v_mov_b32_e32 v24, v0
	v_mov_b32_e32 v25, v0
	v_mov_b32_e32 v26, v0
	v_mov_b32_e32 v27, v0
	v_mov_b32_e32 v32, v0
	v_mov_b32_e32 v33, v0
	v_mov_b32_e32 v34, v0
	v_mov_b32_e32 v35, v0
	v_mov_b32_e32 v40, v0
	v_mov_b32_e32 v41, v0
	v_mov_b32_e32 v42, v0
	v_mov_b32_e32 v43, v0
	v_mov_b32_e32 v48, v0
	v_mov_b32_e32 v49, v0
	v_mov_b32_e32 v50, v0
	v_mov_b32_e32 v51, v0
	v_mov_b32_e32 v56, v0
	v_mov_b32_e32 v57, v0
	v_mov_b32_e32 v58, v0
	v_mov_b32_e32 v59, v0
	v_mov_b32_e32 v60, v0
	v_mov_b32_e32 v61, v0
	v_mov_b32_e32 v62, v0
	v_mov_b32_e32 v63, v0
	v_mov_b32_e32 v64, v0
	v_mov_b32_e32 v65, v0
	v_mov_b32_e32 v66, v0
	v_mov_b32_e32 v67, v0
	v_mov_b32_e32 v68, v0
	v_mov_b32_e32 v69, v0
	v_mov_b32_e32 v70, v0
	v_mov_b32_e32 v71, v0
	v_mov_b32_e32 v76, v0
	v_mov_b32_e32 v77, v0
	v_mov_b32_e32 v78, v0
	v_mov_b32_e32 v79, v0
	v_mov_b32_e32 v86, v0
	v_mov_b32_e32 v87, v0
	v_mov_b32_e32 v88, v0
	v_mov_b32_e32 v89, v0
	v_mov_b32_e32 v94, v0
	v_mov_b32_e32 v95, v0
	v_mov_b32_e32 v96, v0
	v_mov_b32_e32 v97, v0
	v_mov_b32_e32 v102, v0
	v_mov_b32_e32 v103, v0
	v_mov_b32_e32 v104, v0
	v_mov_b32_e32 v105, v0
	v_mov_b32_e32 v110, v0
	v_mov_b32_e32 v111, v0
	v_mov_b32_e32 v112, v0
	v_mov_b32_e32 v113, v0
	v_mov_b32_e32 v118, v0
	v_mov_b32_e32 v119, v0
	v_mov_b32_e32 v120, v0
	v_mov_b32_e32 v121, v0
	v_mov_b32_e32 v72, v0
	v_mov_b32_e32 v73, v0
	v_mov_b32_e32 v74, v0
	v_mov_b32_e32 v75, v0
	v_mov_b32_e32 v82, v0
	v_mov_b32_e32 v83, v0
	v_mov_b32_e32 v84, v0
	v_mov_b32_e32 v85, v0
	v_mov_b32_e32 v90, v0
	v_mov_b32_e32 v91, v0
	v_mov_b32_e32 v92, v0
	v_mov_b32_e32 v93, v0
	v_mov_b32_e32 v98, v0
	v_mov_b32_e32 v99, v0
	v_mov_b32_e32 v100, v0
	v_mov_b32_e32 v101, v0
	v_mov_b32_e32 v106, v0
	v_mov_b32_e32 v107, v0
	v_mov_b32_e32 v108, v0
	v_mov_b32_e32 v109, v0
	v_mov_b32_e32 v114, v0
	v_mov_b32_e32 v115, v0
	v_mov_b32_e32 v116, v0
	v_mov_b32_e32 v117, v0
	v_mov_b32_e32 v122, v0
	v_mov_b32_e32 v123, v0
	v_mov_b32_e32 v124, v0
	v_mov_b32_e32 v125, v0
	v_mov_b32_e32 v126, v0
	v_mov_b32_e32 v127, v0
	v_mov_b32_e32 v128, v0
	v_mov_b32_e32 v129, v0
	v_readfirstlane_b32 s100, v202
	s_nop 3
	s_lshr_b32 s100, s100, 8
	s_cmp_eq_u32 s100, 0
	s_cbranch_scc0 .LBB0_129
.Lcin_A:
	s_add_u32 s48, s46, 0xfffc0080
	s_addc_u32 s49, s47, -1
	s_add_i32 s69, 0, 0x10000
	s_cmp_eq_u32 s68, 12
	s_cselect_b32 s51, s19, s49
	s_cselect_b32 s50, s64, s48
	v_add_u32_e32 v142, s69, v148
	s_cselect_b32 s49, s17, s67
	s_cselect_b32 s48, s65, s66
	s_add_i32 s72, 0, 0x14000
	ds_read_b128 v[150:153], v142
	ds_read_b128 v[154:157], v142 offset:1024
	ds_read_b128 v[158:161], v142 offset:2048
	ds_read_b128 v[176:179], v142 offset:3072
	v_add_u32_e32 v142, s72, v148
	ds_read_b128 v[180:183], v142
	ds_read_b128 v[184:187], v142 offset:1024
	ds_read_b128 v[188:191], v142 offset:2048
	ds_read_b128 v[192:195], v142 offset:3072
	v_lshl_add_u64 v[142:143], s[46:47], 0, v[138:139]
	s_add_i32 m0, s53, 0xc000
	ds_read_b128 v[196:199], v149
	ds_read_b128 v[208:211], v149 offset:1024
	ds_read_b128 v[212:215], v149 offset:2048
	ds_read_b128 v[216:219], v149 offset:3072
	ds_read_b128 v[220:223], v149 offset:4096
	ds_read_b128 v[224:227], v149 offset:5120
	ds_read_b128 v[228:231], v149 offset:6144
	ds_read_b128 v[232:235], v149 offset:7168
	global_load_lds_dwordx4 v[142:143], off
	v_lshl_add_u64 v[142:143], s[46:47], 0, v[140:141]
	s_add_i32 m0, s53, 0xe000
	s_nop 0
	global_load_lds_dwordx4 v[142:143], off
	s_waitcnt lgkmcnt(0)
	s_setprio 1
	s_barrier
; #define PG8_STAGE(bufoff, gbase, voff) do { _Pragma("unroll") for (int _i = 0; _i < 2; ++_i) \
;         __builtin_amdgcn_global_load_lds((const unsigned*)((const char*)(gbase) + (voff)[_i]), (PG8_LAS unsigned*)(lds + (bufoff) + ldsw + _i * 8192), 16, 0, 0); } while (0)
; #define PG8_LDA(dst, b, h) do { _Pragma("unroll") for (int m = 0; m < 4; ++m) _Pragma("unroll") for (int k = 0; k < 2; ++k) dst[m][k] = *(const PG8_LAS bf16x8*)(lds + PG8_SA(b, h) + aoff + m * 2048 + k * 1024); } while (0)
; #define PG8_MMA(ai, bj, At, Bt) do { __builtin_amdgcn_s_setprio(1); _Pragma("unroll") for (int m = 0; m < 4; ++m) _Pragma("unroll") for (int n = 0; n < 2; ++n) _Pragma("unroll") for (int k = 0; k < 2; ++k) \
;         acc[ai][bj][m][n] = __builtin_amdgcn_mfma_f32_16x16x32_bf16(Bt[n][k], At[m][k], acc[ai][bj][m][n], 0, 0, 0); __builtin_amdgcn_s_setprio(0); } while (0)
; #define PG8_WAIT_V(n) asm volatile("s_waitcnt vmcnt(" #n ")" ::: "memory")
; #define PG8_WAIT_L(n) asm volatile("s_waitcnt lgkmcnt(" #n ")" ::: "memory")
; #define PG8_BAR __builtin_amdgcn_s_barrier()
; #define PG8_SCHED __builtin_amdgcn_sched_barrier(0)
; template <class Epi, class Sched, bool ALIGN_EPI = false, bool SP2 = false>
; __device__ __forceinline__ void gemm_phase(PG8_LAS unsigned char* lds, const Gemm g, const Sched& S, const Epi& E) {
;     ...
;             PG8_WAIT_V(8); PG8_WAIT_L(0); PG8_BAR; PG8_MMA(0, 0, At, B0); PG8_MMA(0, 1, At, B1); PG8_BAR; PG8_SCHED;
;             PG8_LDA(At, 0, 1); PG8_STAGE(PG8_SB(0, 0), b2, voffB); PG8_STAGE(PG8_SB(0, 1), b2 + hstep, voffB); PG8_STAGE(PG8_SA(0, 0), a2, voffA);
;             PG8_WAIT_V(8); PG8_WAIT_L(0); PG8_BAR; PG8_MMA(1, 0, At, B0); PG8_MMA(1, 1, At, B1); PG8_BAR; PG8_SCHED;
	v_mfma_f32_16x16x32_bf16 v[126:129], v[150:153], v[196:199], v[126:129]
	v_mfma_f32_16x16x32_bf16 v[122:125], v[158:161], v[196:199], v[122:125]
	v_mfma_f32_16x16x32_bf16 v[114:117], v[150:153], v[212:215], v[114:117]
	v_mfma_f32_16x16x32_bf16 v[106:109], v[158:161], v[212:215], v[106:109]
	v_mfma_f32_16x16x32_bf16 v[98:101], v[150:153], v[220:223], v[98:101]
	v_mfma_f32_16x16x32_bf16 v[90:93], v[158:161], v[220:223], v[90:93]
	v_mfma_f32_16x16x32_bf16 v[82:85], v[150:153], v[228:231], v[82:85]
	v_mfma_f32_16x16x32_bf16 v[72:75], v[158:161], v[228:231], v[72:75]
	v_mfma_f32_16x16x32_bf16 v[126:129], v[154:157], v[208:211], v[126:129]
	v_mfma_f32_16x16x32_bf16 v[122:125], v[176:179], v[208:211], v[122:125]
	v_mfma_f32_16x16x32_bf16 v[114:117], v[154:157], v[216:219], v[114:117]
	v_mfma_f32_16x16x32_bf16 v[106:109], v[176:179], v[216:219], v[106:109]
	v_mfma_f32_16x16x32_bf16 v[98:101], v[154:157], v[224:227], v[98:101]
	v_mfma_f32_16x16x32_bf16 v[90:93], v[176:179], v[224:227], v[90:93]
	v_mfma_f32_16x16x32_bf16 v[82:85], v[154:157], v[232:235], v[82:85]
	v_mfma_f32_16x16x32_bf16 v[72:75], v[176:179], v[232:235], v[72:75]
	v_mfma_f32_16x16x32_bf16 v[118:121], v[180:183], v[196:199], v[118:121]
	v_mfma_f32_16x16x32_bf16 v[110:113], v[188:191], v[196:199], v[110:113]
	v_mfma_f32_16x16x32_bf16 v[102:105], v[180:183], v[212:215], v[102:105]
	v_mfma_f32_16x16x32_bf16 v[94:97], v[188:191], v[212:215], v[94:97]
	v_mfma_f32_16x16x32_bf16 v[86:89], v[180:183], v[220:223], v[86:89]
	v_mfma_f32_16x16x32_bf16 v[76:79], v[188:191], v[220:223], v[76:79]
	v_mfma_f32_16x16x32_bf16 v[68:71], v[180:183], v[228:231], v[68:71]
	v_mfma_f32_16x16x32_bf16 v[64:67], v[188:191], v[228:231], v[64:67]
	v_mfma_f32_16x16x32_bf16 v[118:121], v[184:187], v[208:211], v[118:121]
	v_mfma_f32_16x16x32_bf16 v[110:113], v[192:195], v[208:211], v[110:113]
	v_mfma_f32_16x16x32_bf16 v[102:105], v[184:187], v[216:219], v[102:105]
	v_mfma_f32_16x16x32_bf16 v[94:97], v[192:195], v[216:219], v[94:97]
	v_mfma_f32_16x16x32_bf16 v[86:89], v[184:187], v[224:227], v[86:89]
	v_mfma_f32_16x16x32_bf16 v[76:79], v[192:195], v[224:227], v[76:79]
	v_mfma_f32_16x16x32_bf16 v[68:71], v[184:187], v[232:235], v[68:71]
	v_mfma_f32_16x16x32_bf16 v[64:67], v[192:195], v[232:235], v[64:67]
	s_waitcnt vmcnt(8)
	s_setprio 0
	s_barrier
	s_add_i32 s69, s69, s52
	v_lshl_add_u64 v[142:143], s[48:49], 0, v[134:135]
	s_mov_b32 m0, s69
	ds_read_b128 v[196:199], v149 offset:16384
	ds_read_b128 v[208:211], v149 offset:17408
	ds_read_b128 v[212:215], v149 offset:18432
	ds_read_b128 v[216:219], v149 offset:19456
	ds_read_b128 v[220:223], v149 offset:20480
	ds_read_b128 v[224:227], v149 offset:21504
	ds_read_b128 v[228:231], v149 offset:22528
	ds_read_b128 v[232:235], v149 offset:23552
	global_load_lds_dwordx4 v[142:143], off
	s_add_i32 m0, s69, 0x2000
	s_add_u32 s70, s48, 0x40000
	v_lshl_add_u64 v[146:147], s[48:49], 0, v[130:131]
	s_addc_u32 s71, s49, 0
	s_add_i32 s69, s72, s52
	global_load_lds_dwordx4 v[146:147], off
	v_lshl_add_u64 v[200:201], s[70:71], 0, v[134:135]
	s_mov_b32 m0, s69
	v_lshl_add_u64 v[236:237], s[50:51], 0, v[132:133]
	global_load_lds_dwordx4 v[200:201], off
	v_lshl_add_u64 v[200:201], s[70:71], 0, v[130:131]
	s_add_i32 m0, s69, 0x2000
	s_nop 0
	global_load_lds_dwordx4 v[200:201], off
	v_lshl_add_u64 v[200:201], s[50:51], 0, v[136:137]
	s_mov_b32 m0, s53
	s_nop 0
	global_load_lds_dwordx4 v[200:201], off
	s_mov_b32 m0, s54
	s_nop 0
	global_load_lds_dwordx4 v[236:237], off
	s_waitcnt lgkmcnt(0)
	s_setprio 1
	s_barrier
	v_mfma_f32_16x16x32_bf16 v[60:63], v[150:153], v[196:199], v[60:63]
	v_mfma_f32_16x16x32_bf16 v[56:59], v[158:161], v[196:199], v[56:59]
	v_mfma_f32_16x16x32_bf16 v[48:51], v[150:153], v[212:215], v[48:51]
	v_mfma_f32_16x16x32_bf16 v[40:43], v[158:161], v[212:215], v[40:43]
	v_mfma_f32_16x16x32_bf16 v[32:35], v[150:153], v[220:223], v[32:35]
	v_mfma_f32_16x16x32_bf16 v[24:27], v[158:161], v[220:223], v[24:27]
	v_mfma_f32_16x16x32_bf16 v[16:19], v[150:153], v[228:231], v[16:19]
	v_mfma_f32_16x16x32_bf16 v[8:11], v[158:161], v[228:231], v[8:11]
	v_mfma_f32_16x16x32_bf16 v[60:63], v[154:157], v[208:211], v[60:63]
	v_mfma_f32_16x16x32_bf16 v[56:59], v[176:179], v[208:211], v[56:59]
	v_mfma_f32_16x16x32_bf16 v[48:51], v[154:157], v[216:219], v[48:51]
	v_mfma_f32_16x16x32_bf16 v[40:43], v[176:179], v[216:219], v[40:43]
	v_mfma_f32_16x16x32_bf16 v[32:35], v[154:157], v[224:227], v[32:35]
	v_mfma_f32_16x16x32_bf16 v[24:27], v[176:179], v[224:227], v[24:27]
	v_mfma_f32_16x16x32_bf16 v[16:19], v[154:157], v[232:235], v[16:19]
	v_mfma_f32_16x16x32_bf16 v[8:11], v[176:179], v[232:235], v[8:11]
	v_mfma_f32_16x16x32_bf16 v[52:55], v[180:183], v[196:199], v[52:55]
	v_mfma_f32_16x16x32_bf16 v[44:47], v[188:191], v[196:199], v[44:47]
	v_mfma_f32_16x16x32_bf16 v[36:39], v[180:183], v[212:215], v[36:39]
	v_mfma_f32_16x16x32_bf16 v[28:31], v[188:191], v[212:215], v[28:31]
	v_mfma_f32_16x16x32_bf16 v[20:23], v[180:183], v[220:223], v[20:23]
	v_mfma_f32_16x16x32_bf16 v[12:15], v[188:191], v[220:223], v[12:15]
	v_mfma_f32_16x16x32_bf16 v[4:7], v[180:183], v[228:231], v[4:7]
	v_mfma_f32_16x16x32_bf16 v[0:3], v[188:191], v[228:231], v[0:3]
	v_mfma_f32_16x16x32_bf16 v[52:55], v[184:187], v[208:211], v[52:55]
	v_mfma_f32_16x16x32_bf16 v[44:47], v[192:195], v[208:211], v[44:47]
	v_mfma_f32_16x16x32_bf16 v[36:39], v[184:187], v[216:219], v[36:39]
	v_mfma_f32_16x16x32_bf16 v[28:31], v[192:195], v[216:219], v[28:31]
	v_mfma_f32_16x16x32_bf16 v[20:23], v[184:187], v[224:227], v[20:23]
	v_mfma_f32_16x16x32_bf16 v[12:15], v[192:195], v[224:227], v[12:15]
	v_mfma_f32_16x16x32_bf16 v[4:7], v[184:187], v[232:235], v[4:7]
	v_mfma_f32_16x16x32_bf16 v[0:3], v[192:195], v[232:235], v[0:3]
	s_waitcnt vmcnt(8)
	s_setprio 0
	s_barrier
; #define PG8_STAGE(bufoff, gbase, voff) do { _Pragma("unroll") for (int _i = 0; _i < 2; ++_i) \
;         __builtin_amdgcn_global_load_lds((const unsigned*)((const char*)(gbase) + (voff)[_i]), (PG8_LAS unsigned*)(lds + (bufoff) + ldsw + _i * 8192), 16, 0, 0); } while (0)
; #define PG8_LDA(dst, b, h) do { _Pragma("unroll") for (int m = 0; m < 4; ++m) _Pragma("unroll") for (int k = 0; k < 2; ++k) dst[m][k] = *(const PG8_LAS bf16x8*)(lds + PG8_SA(b, h) + aoff + m * 2048 + k * 1024); } while (0)
; #define PG8_LDB(dst, b, h) do { _Pragma("unroll") for (int n = 0; n < 2; ++n) _Pragma("unroll") for (int k = 0; k < 2; ++k) dst[n][k] = *(const PG8_LAS bf16x8*)(lds + PG8_SB(b, h) + boff + n * 2048 + k * 1024); } while (0)
; #define PG8_MMA(ai, bj, At, Bt) do { __builtin_amdgcn_s_setprio(1); _Pragma("unroll") for (int m = 0; m < 4; ++m) _Pragma("unroll") for (int n = 0; n < 2; ++n) _Pragma("unroll") for (int k = 0; k < 2; ++k) \
;         acc[ai][bj][m][n] = __builtin_amdgcn_mfma_f32_16x16x32_bf16(Bt[n][k], At[m][k], acc[ai][bj][m][n], 0, 0, 0); __builtin_amdgcn_s_setprio(0); } while (0)
; #define PG8_WAIT_V(n) asm volatile("s_waitcnt vmcnt(" #n ")" ::: "memory")
; #define PG8_WAIT_L(n) asm volatile("s_waitcnt lgkmcnt(" #n ")" ::: "memory")
; #define PG8_BAR __builtin_amdgcn_s_barrier()
; #define PG8_SCHED __builtin_amdgcn_sched_barrier(0)
; template <class Epi, class Sched, bool ALIGN_EPI = false, bool SP2 = false>
; __device__ __forceinline__ void gemm_phase(PG8_LAS unsigned char* lds, const Gemm g, const Sched& S, const Epi& E) {
;     ...
;             PG8_LDB(B0, 1, 0); PG8_LDB(B1, 1, 1); PG8_SCHED; PG8_LDA(At, 1, 0); PG8_STAGE(PG8_SA(0, 1), a2 + hstep, voffA);
;             PG8_WAIT_V(8); PG8_WAIT_L(0); PG8_BAR; PG8_MMA(0, 0, At, B0); PG8_MMA(0, 1, At, B1); PG8_BAR; PG8_SCHED;
	s_add_i32 s69, 0, 0x18000
	v_add_u32_e32 v144, s69, v148
	s_add_i32 s70, 0, 0x1c000
	ds_read_b128 v[150:153], v144
	ds_read_b128 v[154:157], v144 offset:1024
	ds_read_b128 v[158:161], v144 offset:2048
	ds_read_b128 v[176:179], v144 offset:3072
	v_add_u32_e32 v144, s70, v148
	ds_read_b128 v[180:183], v144
	ds_read_b128 v[184:187], v144 offset:1024
	ds_read_b128 v[188:191], v144 offset:2048
	ds_read_b128 v[192:195], v144 offset:3072
	s_add_u32 s50, s50, 0x40000
	s_addc_u32 s51, s51, 0
	s_mov_b32 m0, s55
	v_lshl_add_u64 v[238:239], s[50:51], 0, v[136:137]
	ds_read_b128 v[196:199], v149 offset:32768
	ds_read_b128 v[208:211], v149 offset:33792
	ds_read_b128 v[212:215], v149 offset:34816
	ds_read_b128 v[216:219], v149 offset:35840
	ds_read_b128 v[220:223], v149 offset:36864
	ds_read_b128 v[224:227], v149 offset:37888
	ds_read_b128 v[228:231], v149 offset:38912
	ds_read_b128 v[232:235], v149 offset:39936
	global_load_lds_dwordx4 v[238:239], off
	v_lshl_add_u64 v[238:239], s[50:51], 0, v[132:133]
	s_mov_b32 m0, s56
	s_nop 0
	global_load_lds_dwordx4 v[238:239], off
	s_waitcnt lgkmcnt(0)
	s_setprio 1
	s_barrier
	v_mfma_f32_16x16x32_bf16 v[126:129], v[150:153], v[196:199], v[126:129]
	v_mfma_f32_16x16x32_bf16 v[122:125], v[158:161], v[196:199], v[122:125]
	v_mfma_f32_16x16x32_bf16 v[114:117], v[150:153], v[212:215], v[114:117]
	v_mfma_f32_16x16x32_bf16 v[106:109], v[158:161], v[212:215], v[106:109]
	v_mfma_f32_16x16x32_bf16 v[98:101], v[150:153], v[220:223], v[98:101]
	v_mfma_f32_16x16x32_bf16 v[90:93], v[158:161], v[220:223], v[90:93]
	v_mfma_f32_16x16x32_bf16 v[82:85], v[150:153], v[228:231], v[82:85]
	v_mfma_f32_16x16x32_bf16 v[72:75], v[158:161], v[228:231], v[72:75]
	v_mfma_f32_16x16x32_bf16 v[126:129], v[154:157], v[208:211], v[126:129]
	v_mfma_f32_16x16x32_bf16 v[122:125], v[176:179], v[208:211], v[122:125]
	v_mfma_f32_16x16x32_bf16 v[114:117], v[154:157], v[216:219], v[114:117]
	v_mfma_f32_16x16x32_bf16 v[106:109], v[176:179], v[216:219], v[106:109]
	v_mfma_f32_16x16x32_bf16 v[98:101], v[154:157], v[224:227], v[98:101]
	v_mfma_f32_16x16x32_bf16 v[90:93], v[176:179], v[224:227], v[90:93]
	v_mfma_f32_16x16x32_bf16 v[82:85], v[154:157], v[232:235], v[82:85]
	v_mfma_f32_16x16x32_bf16 v[72:75], v[176:179], v[232:235], v[72:75]
	v_mfma_f32_16x16x32_bf16 v[118:121], v[180:183], v[196:199], v[118:121]
	v_mfma_f32_16x16x32_bf16 v[110:113], v[188:191], v[196:199], v[110:113]
	v_mfma_f32_16x16x32_bf16 v[102:105], v[180:183], v[212:215], v[102:105]
	v_mfma_f32_16x16x32_bf16 v[94:97], v[188:191], v[212:215], v[94:97]
	v_mfma_f32_16x16x32_bf16 v[86:89], v[180:183], v[220:223], v[86:89]
	v_mfma_f32_16x16x32_bf16 v[76:79], v[188:191], v[220:223], v[76:79]
	v_mfma_f32_16x16x32_bf16 v[68:71], v[180:183], v[228:231], v[68:71]
	v_mfma_f32_16x16x32_bf16 v[64:67], v[188:191], v[228:231], v[64:67]
	v_mfma_f32_16x16x32_bf16 v[118:121], v[184:187], v[208:211], v[118:121]
	v_mfma_f32_16x16x32_bf16 v[110:113], v[192:195], v[208:211], v[110:113]
	v_mfma_f32_16x16x32_bf16 v[102:105], v[184:187], v[216:219], v[102:105]
	v_mfma_f32_16x16x32_bf16 v[94:97], v[192:195], v[216:219], v[94:97]
	v_mfma_f32_16x16x32_bf16 v[86:89], v[184:187], v[224:227], v[86:89]
	v_mfma_f32_16x16x32_bf16 v[76:79], v[192:195], v[224:227], v[76:79]
	v_mfma_f32_16x16x32_bf16 v[68:71], v[184:187], v[232:235], v[68:71]
	v_mfma_f32_16x16x32_bf16 v[64:67], v[192:195], v[232:235], v[64:67]
	s_waitcnt vmcnt(8)
	s_setprio 0
	s_barrier
; #define PG8_STAGE(bufoff, gbase, voff) do { _Pragma("unroll") for (int _i = 0; _i < 2; ++_i) \
;         __builtin_amdgcn_global_load_lds((const unsigned*)((const char*)(gbase) + (voff)[_i]), (PG8_LAS unsigned*)(lds + (bufoff) + ldsw + _i * 8192), 16, 0, 0); } while (0)
; #define PG8_LDA(dst, b, h) do { _Pragma("unroll") for (int m = 0; m < 4; ++m) _Pragma("unroll") for (int k = 0; k < 2; ++k) dst[m][k] = *(const PG8_LAS bf16x8*)(lds + PG8_SA(b, h) + aoff + m * 2048 + k * 1024); } while (0)
; #define PG8_MMA(ai, bj, At, Bt) do { __builtin_amdgcn_s_setprio(1); _Pragma("unroll") for (int m = 0; m < 4; ++m) _Pragma("unroll") for (int n = 0; n < 2; ++n) _Pragma("unroll") for (int k = 0; k < 2; ++k) \
;         acc[ai][bj][m][n] = __builtin_amdgcn_mfma_f32_16x16x32_bf16(Bt[n][k], At[m][k], acc[ai][bj][m][n], 0, 0, 0); __builtin_amdgcn_s_setprio(0); } while (0)
; #define PG8_WAIT_V(n) asm volatile("s_waitcnt vmcnt(" #n ")" ::: "memory")
; #define PG8_WAIT_L(n) asm volatile("s_waitcnt lgkmcnt(" #n ")" ::: "memory")
; #define PG8_BAR __builtin_amdgcn_s_barrier()
; #define PG8_SCHED __builtin_amdgcn_sched_barrier(0)
; template <class Epi, class Sched, bool ALIGN_EPI = false, bool SP2 = false>
; __device__ __forceinline__ void gemm_phase(PG8_LAS unsigned char* lds, const Gemm g, const Sched& S, const Epi& E) {
;     ...
;         for (int t = 0; t < nt; t += 2) {
;     ...
;             PG8_LDA(At, 1, 1); PG8_STAGE(PG8_SB(1, 0), b3, voffB); PG8_STAGE(PG8_SB(1, 1), b3 + hstep, voffB); PG8_STAGE(PG8_SA(1, 0), a3, voffA);
;             PG8_WAIT_V(8); PG8_WAIT_L(0); PG8_BAR; PG8_MMA(1, 0, At, B0); PG8_MMA(1, 1, At, B1); PG8_BAR; PG8_SCHED;
	s_add_i32 s50, s69, s52
	v_lshl_add_u64 v[142:143], v[142:143], 0, s[40:41]
	s_mov_b32 m0, s50
	ds_read_b128 v[196:199], v149 offset:49152
	ds_read_b128 v[208:211], v149 offset:50176
	ds_read_b128 v[212:215], v149 offset:51200
	ds_read_b128 v[216:219], v149 offset:52224
	ds_read_b128 v[220:223], v149 offset:53248
	ds_read_b128 v[224:227], v149 offset:54272
	ds_read_b128 v[228:231], v149 offset:55296
	ds_read_b128 v[232:235], v149 offset:56320
	global_load_lds_dwordx4 v[142:143], off
	s_add_i32 m0, s50, 0x2000
	s_add_u32 s48, s48, 0x40080
	v_lshl_add_u64 v[142:143], v[146:147], 0, s[40:41]
	s_addc_u32 s49, s49, 0
	s_add_i32 s50, s70, s52
	global_load_lds_dwordx4 v[142:143], off
	v_lshl_add_u64 v[142:143], s[48:49], 0, v[134:135]
	s_mov_b32 m0, s50
	s_nop 0
	global_load_lds_dwordx4 v[142:143], off
	v_lshl_add_u64 v[142:143], s[48:49], 0, v[130:131]
	s_add_i32 m0, s50, 0x2000
	s_nop 0
	global_load_lds_dwordx4 v[142:143], off
	v_lshl_add_u64 v[142:143], v[200:201], 0, s[40:41]
	s_mov_b32 m0, s59
	s_nop 0
	global_load_lds_dwordx4 v[142:143], off
	v_lshl_add_u64 v[142:143], v[236:237], 0, s[40:41]
	s_mov_b32 m0, s60
	s_nop 0
	global_load_lds_dwordx4 v[142:143], off
	s_waitcnt lgkmcnt(0)
	s_setprio 1
	s_barrier
	v_mfma_f32_16x16x32_bf16 v[60:63], v[150:153], v[196:199], v[60:63]
	v_mfma_f32_16x16x32_bf16 v[56:59], v[158:161], v[196:199], v[56:59]
	v_mfma_f32_16x16x32_bf16 v[48:51], v[150:153], v[212:215], v[48:51]
	v_mfma_f32_16x16x32_bf16 v[40:43], v[158:161], v[212:215], v[40:43]
	v_mfma_f32_16x16x32_bf16 v[32:35], v[150:153], v[220:223], v[32:35]
	v_mfma_f32_16x16x32_bf16 v[24:27], v[158:161], v[220:223], v[24:27]
	v_mfma_f32_16x16x32_bf16 v[16:19], v[150:153], v[228:231], v[16:19]
	v_mfma_f32_16x16x32_bf16 v[8:11], v[158:161], v[228:231], v[8:11]
	v_mfma_f32_16x16x32_bf16 v[60:63], v[154:157], v[208:211], v[60:63]
	v_mfma_f32_16x16x32_bf16 v[56:59], v[176:179], v[208:211], v[56:59]
	v_mfma_f32_16x16x32_bf16 v[48:51], v[154:157], v[216:219], v[48:51]
	v_mfma_f32_16x16x32_bf16 v[40:43], v[176:179], v[216:219], v[40:43]
	v_mfma_f32_16x16x32_bf16 v[32:35], v[154:157], v[224:227], v[32:35]
	v_mfma_f32_16x16x32_bf16 v[24:27], v[176:179], v[224:227], v[24:27]
	v_mfma_f32_16x16x32_bf16 v[16:19], v[154:157], v[232:235], v[16:19]
	v_mfma_f32_16x16x32_bf16 v[8:11], v[176:179], v[232:235], v[8:11]
	v_mfma_f32_16x16x32_bf16 v[52:55], v[180:183], v[196:199], v[52:55]
	v_mfma_f32_16x16x32_bf16 v[44:47], v[188:191], v[196:199], v[44:47]
	v_mfma_f32_16x16x32_bf16 v[36:39], v[180:183], v[212:215], v[36:39]
	v_mfma_f32_16x16x32_bf16 v[28:31], v[188:191], v[212:215], v[28:31]
	v_mfma_f32_16x16x32_bf16 v[20:23], v[180:183], v[220:223], v[20:23]
	v_mfma_f32_16x16x32_bf16 v[12:15], v[188:191], v[220:223], v[12:15]
	v_mfma_f32_16x16x32_bf16 v[4:7], v[180:183], v[228:231], v[4:7]
	v_mfma_f32_16x16x32_bf16 v[0:3], v[188:191], v[228:231], v[0:3]
	v_mfma_f32_16x16x32_bf16 v[52:55], v[184:187], v[208:211], v[52:55]
	v_mfma_f32_16x16x32_bf16 v[44:47], v[192:195], v[208:211], v[44:47]
	v_mfma_f32_16x16x32_bf16 v[36:39], v[184:187], v[216:219], v[36:39]
	v_mfma_f32_16x16x32_bf16 v[28:31], v[192:195], v[216:219], v[28:31]
	v_mfma_f32_16x16x32_bf16 v[20:23], v[184:187], v[224:227], v[20:23]
	v_mfma_f32_16x16x32_bf16 v[12:15], v[192:195], v[224:227], v[12:15]
	v_mfma_f32_16x16x32_bf16 v[4:7], v[184:187], v[232:235], v[4:7]
	v_mfma_f32_16x16x32_bf16 v[0:3], v[192:195], v[232:235], v[0:3]
	s_waitcnt vmcnt(8)
	s_setprio 0
	s_barrier
	s_add_i32 s68, s68, 2
	s_add_u32 s46, s46, 0x100
	s_addc_u32 s47, s47, 0
	s_add_u32 s66, s66, 0x100
	s_addc_u32 s67, s67, 0
	s_cmp_gt_u32 s68, 13
	s_cbranch_scc0 .Lcin_A
	s_branch .Lcin_done

; #define PG8_BAR __builtin_amdgcn_s_barrier()
; template <class Epi, class Sched, bool ALIGN_EPI = false, bool SP2 = false>
; __device__ __forceinline__ void gemm_phase(PG8_LAS unsigned char* lds, const Gemm g, const Sched& S, const Epi& E) {
;     ...
;         if constexpr (ALIGN_EPI) { if (wr == 0) PG8_BAR; }
.Lcin_done:
	s_and_b64 vcc, exec, s[14:15]
	s_cbranch_vccz .LBB0_132
	s_barrier

; #define PG8_STAGE(bufoff, gbase, voff) do { _Pragma("unroll") for (int _i = 0; _i < 2; ++_i) \
;         __builtin_amdgcn_global_load_lds((const unsigned*)((const char*)(gbase) + (voff)[_i]), (PG8_LAS unsigned*)(lds + (bufoff) + ldsw + _i * 8192), 16, 0, 0); } while (0)
; #define PG8_LDA(dst, b, h) do { _Pragma("unroll") for (int m = 0; m < 4; ++m) _Pragma("unroll") for (int k = 0; k < 2; ++k) dst[m][k] = *(const PG8_LAS bf16x8*)(lds + PG8_SA(b, h) + aoff + m * 2048 + k * 1024); } while (0)
; #define PG8_LDB(dst, b, h) do { _Pragma("unroll") for (int n = 0; n < 2; ++n) _Pragma("unroll") for (int k = 0; k < 2; ++k) dst[n][k] = *(const PG8_LAS bf16x8*)(lds + PG8_SB(b, h) + boff + n * 2048 + k * 1024); } while (0)
; #define PG8_MMA(ai, bj, At, Bt) do { __builtin_amdgcn_s_setprio(1); _Pragma("unroll") for (int m = 0; m < 4; ++m) _Pragma("unroll") for (int n = 0; n < 2; ++n) _Pragma("unroll") for (int k = 0; k < 2; ++k) \
;         acc[ai][bj][m][n] = __builtin_amdgcn_mfma_f32_16x16x32_bf16(Bt[n][k], At[m][k], acc[ai][bj][m][n], 0, 0, 0); __builtin_amdgcn_s_setprio(0); } while (0)
; #define PG8_WAIT_V(n) asm volatile("s_waitcnt vmcnt(" #n ")" ::: "memory")
; #define PG8_WAIT_L(n) asm volatile("s_waitcnt lgkmcnt(" #n ")" ::: "memory")
; #define PG8_BAR __builtin_amdgcn_s_barrier()
; #define PG8_SCHED __builtin_amdgcn_sched_barrier(0)
; template <class Epi, class Sched, bool ALIGN_EPI = false, bool SP2 = false>
; __device__ __forceinline__ void gemm_phase(PG8_LAS unsigned char* lds, const Gemm g, const Sched& S, const Epi& E) {
;     ...
;             PG8_LDB(B0, 0, 0); PG8_LDB(B1, 0, 1); PG8_SCHED; PG8_LDA(At, 0, 0); PG8_STAGE(PG8_SA(1, 1), a1 + hstep, voffA);
;             PG8_WAIT_V(8); PG8_WAIT_L(0); PG8_BAR; PG8_MMA(0, 0, At, B0); PG8_MMA(0, 1, At, B1); PG8_BAR; PG8_SCHED;
;     ...
; #pragma unroll
;         for (int a = 0; a < 2; ++a)
; #pragma unroll
;             for (int b = 0; b < 2; ++b)
; #pragma unroll
;                 for (int m = 0; m < 4; ++m)
; #pragma unroll
;                     for (int n = 0; n < 2; ++n) acc[a][b][m][n] = (f32x4){0.f, 0.f, 0.f, 0.f};
;         cur = nxt; cA = nA; cB = nB; ++ui;
.LBB0_158:
	s_ashr_i32 s17, s16, 31
	s_lshl_b64 s[44:45], s[16:17], 19
	s_cmp_eq_u32 s65, 0
	s_cselect_b32 s17, s30, s52
	s_cselect_b32 s5, s31, s53
	s_cselect_b32 s50, s38, s30
	s_cselect_b32 s51, s39, s31
	s_add_u32 s44, s17, s44
	s_addc_u32 s45, s5, s45
	s_and_b64 s[46:47], s[42:43], exec
	s_cselect_b32 s5, s45, s7
	s_cselect_b32 s17, s44, s6
	s_ashr_i32 s19, s18, 31
	s_lshl_b64 s[46:47], s[18:19], 19
	s_add_u32 s46, s50, s46
	s_addc_u32 s47, s51, s47
	s_and_b64 s[50:51], s[42:43], exec
	s_cselect_b32 s19, s47, s49
	s_cselect_b32 s67, s46, s48
	s_add_u32 s6, s6, 0x40080
	s_addc_u32 s7, s7, 0
	s_add_u32 s68, s48, 0x100
	v_mov_b32_e32 v0, 0
	s_addc_u32 s69, s49, 0
	s_mov_b32 s70, -2
	v_mov_b32_e32 v1, v0
	v_mov_b32_e32 v2, v0
	v_mov_b32_e32 v3, v0
	v_mov_b32_e32 v4, v0
	v_mov_b32_e32 v5, v0
	v_mov_b32_e32 v6, v0
	v_mov_b32_e32 v7, v0
	v_mov_b32_e32 v16, v0
	v_mov_b32_e32 v17, v0
	v_mov_b32_e32 v18, v0
	v_mov_b32_e32 v19, v0
	v_mov_b32_e32 v20, v0
	v_mov_b32_e32 v21, v0
	v_mov_b32_e32 v22, v0
	v_mov_b32_e32 v23, v0
	v_mov_b32_e32 v32, v0
	v_mov_b32_e32 v33, v0
	v_mov_b32_e32 v34, v0
	v_mov_b32_e32 v35, v0
	v_mov_b32_e32 v36, v0
	v_mov_b32_e32 v37, v0
	v_mov_b32_e32 v38, v0
	v_mov_b32_e32 v39, v0
	v_mov_b32_e32 v48, v0
	v_mov_b32_e32 v49, v0
	v_mov_b32_e32 v50, v0
	v_mov_b32_e32 v51, v0
	v_mov_b32_e32 v52, v0
	v_mov_b32_e32 v53, v0
	v_mov_b32_e32 v54, v0
	v_mov_b32_e32 v55, v0
	v_mov_b32_e32 v8, v0
	v_mov_b32_e32 v9, v0
	v_mov_b32_e32 v10, v0
	v_mov_b32_e32 v11, v0
	v_mov_b32_e32 v12, v0
	v_mov_b32_e32 v13, v0
	v_mov_b32_e32 v14, v0
	v_mov_b32_e32 v15, v0
	v_mov_b32_e32 v24, v0
	v_mov_b32_e32 v25, v0
	v_mov_b32_e32 v26, v0
	v_mov_b32_e32 v27, v0
	v_mov_b32_e32 v28, v0
	v_mov_b32_e32 v29, v0
	v_mov_b32_e32 v30, v0
	v_mov_b32_e32 v31, v0
	v_mov_b32_e32 v40, v0
	v_mov_b32_e32 v41, v0
	v_mov_b32_e32 v42, v0
	v_mov_b32_e32 v43, v0
	v_mov_b32_e32 v44, v0
	v_mov_b32_e32 v45, v0
	v_mov_b32_e32 v46, v0
	v_mov_b32_e32 v47, v0
	v_mov_b32_e32 v56, v0
	v_mov_b32_e32 v57, v0
	v_mov_b32_e32 v58, v0
	v_mov_b32_e32 v59, v0
	v_mov_b32_e32 v60, v0
	v_mov_b32_e32 v61, v0
	v_mov_b32_e32 v62, v0
	v_mov_b32_e32 v63, v0
	v_mov_b32_e32 v64, v0
	v_mov_b32_e32 v65, v0
	v_mov_b32_e32 v66, v0
	v_mov_b32_e32 v67, v0
	v_mov_b32_e32 v68, v0
	v_mov_b32_e32 v69, v0
	v_mov_b32_e32 v70, v0
	v_mov_b32_e32 v71, v0
	v_mov_b32_e32 v82, v0
	v_mov_b32_e32 v83, v0
	v_mov_b32_e32 v84, v0
	v_mov_b32_e32 v85, v0
	v_mov_b32_e32 v86, v0
	v_mov_b32_e32 v87, v0
	v_mov_b32_e32 v88, v0
	v_mov_b32_e32 v89, v0
	v_mov_b32_e32 v98, v0
	v_mov_b32_e32 v99, v0
	v_mov_b32_e32 v100, v0
	v_mov_b32_e32 v101, v0
	v_mov_b32_e32 v102, v0
	v_mov_b32_e32 v103, v0
	v_mov_b32_e32 v104, v0
	v_mov_b32_e32 v105, v0
	v_mov_b32_e32 v114, v0
	v_mov_b32_e32 v115, v0
	v_mov_b32_e32 v116, v0
	v_mov_b32_e32 v117, v0
	v_mov_b32_e32 v118, v0
	v_mov_b32_e32 v119, v0
	v_mov_b32_e32 v120, v0
	v_mov_b32_e32 v121, v0
	v_mov_b32_e32 v72, v0
	v_mov_b32_e32 v73, v0
	v_mov_b32_e32 v74, v0
	v_mov_b32_e32 v75, v0
	v_mov_b32_e32 v76, v0
	v_mov_b32_e32 v77, v0
	v_mov_b32_e32 v78, v0
	v_mov_b32_e32 v79, v0
	v_mov_b32_e32 v90, v0
	v_mov_b32_e32 v91, v0
	v_mov_b32_e32 v92, v0
	v_mov_b32_e32 v93, v0
	v_mov_b32_e32 v94, v0
	v_mov_b32_e32 v95, v0
	v_mov_b32_e32 v96, v0
	v_mov_b32_e32 v97, v0
	v_mov_b32_e32 v106, v0
	v_mov_b32_e32 v107, v0
	v_mov_b32_e32 v108, v0
	v_mov_b32_e32 v109, v0
	v_mov_b32_e32 v110, v0
	v_mov_b32_e32 v111, v0
	v_mov_b32_e32 v112, v0
	v_mov_b32_e32 v113, v0
	v_mov_b32_e32 v122, v0
	v_mov_b32_e32 v123, v0
	v_mov_b32_e32 v124, v0
	v_mov_b32_e32 v125, v0
	v_mov_b32_e32 v126, v0
	v_mov_b32_e32 v127, v0
	v_mov_b32_e32 v128, v0
	v_mov_b32_e32 v129, v0
	v_readfirstlane_b32 s100, v202
	s_nop 3
	s_lshr_b32 s100, s100, 8
	s_cmp_eq_u32 s100, 0
	s_cbranch_scc0 .LBB0_159
.Lqkv_A:
	s_add_u32 s48, s6, 0xfffc0080
	s_addc_u32 s49, s7, -1
	s_add_i32 s71, 0, 0x10000
	s_cmp_eq_u32 s70, 12
	s_cselect_b32 s51, s5, s49
	s_cselect_b32 s50, s17, s48
	s_cselect_b32 s49, s19, s69
	s_cselect_b32 s48, s67, s68
	s_add_i32 s74, 0, 0x14000
	v_add_u32_e32 v142, s71, v199
	v_add_u32_e32 v158, s74, v199
	ds_read_b128 v[130:133], v142
	ds_read_b128 v[134:137], v142 offset:1024
	ds_read_b128 v[138:141], v142 offset:2048
	s_waitcnt lgkmcnt(0)
	ds_read_b128 v[142:145], v142 offset:3072
	ds_read_b128 v[146:149], v158
	ds_read_b128 v[150:153], v158 offset:1024
	ds_read_b128 v[154:157], v158 offset:2048
	ds_read_b128 v[158:161], v158 offset:3072
	v_lshl_add_u64 v[196:197], s[6:7], 0, v[184:185]
	s_add_i32 m0, s11, 0xc000
	ds_read_b128 v[188:191], v200
	ds_read_b128 v[192:195], v200 offset:1024
	ds_read_b128 v[208:211], v200 offset:2048
	ds_read_b128 v[212:215], v200 offset:3072
	ds_read_b128 v[216:219], v200 offset:4096
	ds_read_b128 v[220:223], v200 offset:5120
	ds_read_b128 v[224:227], v200 offset:6144
	ds_read_b128 v[228:231], v200 offset:7168
	global_load_lds_dwordx4 v[196:197], off
	v_lshl_add_u64 v[196:197], s[6:7], 0, v[186:187]
	s_add_i32 m0, s11, 0xe000
	s_nop 0
	global_load_lds_dwordx4 v[196:197], off
	s_waitcnt lgkmcnt(0)
	s_setprio 1
	s_barrier
; #define PG8_STAGE(bufoff, gbase, voff) do { _Pragma("unroll") for (int _i = 0; _i < 2; ++_i) \
;         __builtin_amdgcn_global_load_lds((const unsigned*)((const char*)(gbase) + (voff)[_i]), (PG8_LAS unsigned*)(lds + (bufoff) + ldsw + _i * 8192), 16, 0, 0); } while (0)
; #define PG8_LDA(dst, b, h) do { _Pragma("unroll") for (int m = 0; m < 4; ++m) _Pragma("unroll") for (int k = 0; k < 2; ++k) dst[m][k] = *(const PG8_LAS bf16x8*)(lds + PG8_SA(b, h) + aoff + m * 2048 + k * 1024); } while (0)
; #define PG8_MMA(ai, bj, At, Bt) do { __builtin_amdgcn_s_setprio(1); _Pragma("unroll") for (int m = 0; m < 4; ++m) _Pragma("unroll") for (int n = 0; n < 2; ++n) _Pragma("unroll") for (int k = 0; k < 2; ++k) \
;         acc[ai][bj][m][n] = __builtin_amdgcn_mfma_f32_16x16x32_bf16(Bt[n][k], At[m][k], acc[ai][bj][m][n], 0, 0, 0); __builtin_amdgcn_s_setprio(0); } while (0)
; #define PG8_WAIT_V(n) asm volatile("s_waitcnt vmcnt(" #n ")" ::: "memory")
; #define PG8_WAIT_L(n) asm volatile("s_waitcnt lgkmcnt(" #n ")" ::: "memory")
; #define PG8_BAR __builtin_amdgcn_s_barrier()
; #define PG8_SCHED __builtin_amdgcn_sched_barrier(0)
; template <class Epi, class Sched, bool ALIGN_EPI = false, bool SP2 = false>
; __device__ __forceinline__ void gemm_phase(PG8_LAS unsigned char* lds, const Gemm g, const Sched& S, const Epi& E) {
;     ...
;             PG8_WAIT_V(8); PG8_WAIT_L(0); PG8_BAR; PG8_MMA(0, 0, At, B0); PG8_MMA(0, 1, At, B1); PG8_BAR; PG8_SCHED;
;             PG8_LDA(At, 0, 1); PG8_STAGE(PG8_SB(0, 0), b2, voffB); PG8_STAGE(PG8_SB(0, 1), b2 + hstep, voffB); PG8_STAGE(PG8_SA(0, 0), a2, voffA);
;             PG8_WAIT_V(8); PG8_WAIT_L(0); PG8_BAR; PG8_MMA(1, 0, At, B0); PG8_MMA(1, 1, At, B1); PG8_BAR; PG8_SCHED;
	v_mfma_f32_16x16x32_bf16 v[126:129], v[130:133], v[188:191], v[126:129]
	v_mfma_f32_16x16x32_bf16 v[122:125], v[138:141], v[188:191], v[122:125]
	v_mfma_f32_16x16x32_bf16 v[110:113], v[130:133], v[208:211], v[110:113]
	v_mfma_f32_16x16x32_bf16 v[106:109], v[138:141], v[208:211], v[106:109]
	v_mfma_f32_16x16x32_bf16 v[94:97], v[130:133], v[216:219], v[94:97]
	v_mfma_f32_16x16x32_bf16 v[90:93], v[138:141], v[216:219], v[90:93]
	v_mfma_f32_16x16x32_bf16 v[76:79], v[130:133], v[224:227], v[76:79]
	v_mfma_f32_16x16x32_bf16 v[72:75], v[138:141], v[224:227], v[72:75]
	v_mfma_f32_16x16x32_bf16 v[126:129], v[134:137], v[192:195], v[126:129]
	v_mfma_f32_16x16x32_bf16 v[122:125], v[142:145], v[192:195], v[122:125]
	v_mfma_f32_16x16x32_bf16 v[110:113], v[134:137], v[212:215], v[110:113]
	v_mfma_f32_16x16x32_bf16 v[106:109], v[142:145], v[212:215], v[106:109]
	v_mfma_f32_16x16x32_bf16 v[94:97], v[134:137], v[220:223], v[94:97]
	v_mfma_f32_16x16x32_bf16 v[90:93], v[142:145], v[220:223], v[90:93]
	v_mfma_f32_16x16x32_bf16 v[76:79], v[134:137], v[228:231], v[76:79]
	v_mfma_f32_16x16x32_bf16 v[72:75], v[142:145], v[228:231], v[72:75]
	v_mfma_f32_16x16x32_bf16 v[118:121], v[146:149], v[188:191], v[118:121]
	v_mfma_f32_16x16x32_bf16 v[114:117], v[154:157], v[188:191], v[114:117]
	v_mfma_f32_16x16x32_bf16 v[102:105], v[146:149], v[208:211], v[102:105]
	v_mfma_f32_16x16x32_bf16 v[98:101], v[154:157], v[208:211], v[98:101]
	v_mfma_f32_16x16x32_bf16 v[86:89], v[146:149], v[216:219], v[86:89]
	v_mfma_f32_16x16x32_bf16 v[82:85], v[154:157], v[216:219], v[82:85]
	v_mfma_f32_16x16x32_bf16 v[68:71], v[146:149], v[224:227], v[68:71]
	v_mfma_f32_16x16x32_bf16 v[64:67], v[154:157], v[224:227], v[64:67]
	v_mfma_f32_16x16x32_bf16 v[118:121], v[150:153], v[192:195], v[118:121]
	v_mfma_f32_16x16x32_bf16 v[114:117], v[158:161], v[192:195], v[114:117]
	v_mfma_f32_16x16x32_bf16 v[102:105], v[150:153], v[212:215], v[102:105]
	v_mfma_f32_16x16x32_bf16 v[98:101], v[158:161], v[212:215], v[98:101]
	v_mfma_f32_16x16x32_bf16 v[86:89], v[150:153], v[220:223], v[86:89]
	v_mfma_f32_16x16x32_bf16 v[82:85], v[158:161], v[220:223], v[82:85]
	v_mfma_f32_16x16x32_bf16 v[68:71], v[150:153], v[228:231], v[68:71]
	v_mfma_f32_16x16x32_bf16 v[64:67], v[158:161], v[228:231], v[64:67]
	s_waitcnt vmcnt(8)
	s_setprio 0
	s_barrier
	s_add_i32 s71, s71, s54
	v_lshl_add_u64 v[196:197], s[48:49], 0, v[178:179]
	s_mov_b32 m0, s71
	ds_read_b128 v[188:191], v200 offset:16384
	ds_read_b128 v[192:195], v200 offset:17408
	ds_read_b128 v[208:211], v200 offset:18432
	ds_read_b128 v[212:215], v200 offset:19456
	ds_read_b128 v[216:219], v200 offset:20480
	ds_read_b128 v[220:223], v200 offset:21504
	ds_read_b128 v[224:227], v200 offset:22528
	ds_read_b128 v[228:231], v200 offset:23552
	global_load_lds_dwordx4 v[196:197], off
	s_add_i32 m0, s71, 0x2000
	s_add_u32 s72, s48, 0x40000
	v_lshl_add_u64 v[232:233], s[48:49], 0, v[182:183]
	s_addc_u32 s73, s49, 0
	s_add_i32 s71, s74, s54
	global_load_lds_dwordx4 v[232:233], off
	v_lshl_add_u64 v[234:235], s[72:73], 0, v[178:179]
	s_mov_b32 m0, s71
	v_lshl_add_u64 v[236:237], s[50:51], 0, v[180:181]
	global_load_lds_dwordx4 v[234:235], off
	v_lshl_add_u64 v[234:235], s[72:73], 0, v[182:183]
	s_add_i32 m0, s71, 0x2000
	s_nop 0
	global_load_lds_dwordx4 v[234:235], off
	v_lshl_add_u64 v[234:235], s[50:51], 0, v[176:177]
	s_mov_b32 m0, s11
	s_nop 0
	global_load_lds_dwordx4 v[234:235], off
	s_mov_b32 m0, s55
	s_nop 0
	global_load_lds_dwordx4 v[236:237], off
	s_waitcnt lgkmcnt(0)
	s_setprio 1
	s_barrier
	v_mfma_f32_16x16x32_bf16 v[60:63], v[130:133], v[188:191], v[60:63]
	v_mfma_f32_16x16x32_bf16 v[56:59], v[138:141], v[188:191], v[56:59]
	v_mfma_f32_16x16x32_bf16 v[44:47], v[130:133], v[208:211], v[44:47]
	v_mfma_f32_16x16x32_bf16 v[40:43], v[138:141], v[208:211], v[40:43]
	v_mfma_f32_16x16x32_bf16 v[28:31], v[130:133], v[216:219], v[28:31]
	v_mfma_f32_16x16x32_bf16 v[24:27], v[138:141], v[216:219], v[24:27]
	v_mfma_f32_16x16x32_bf16 v[12:15], v[130:133], v[224:227], v[12:15]
	v_mfma_f32_16x16x32_bf16 v[8:11], v[138:141], v[224:227], v[8:11]
	v_mfma_f32_16x16x32_bf16 v[60:63], v[134:137], v[192:195], v[60:63]
	v_mfma_f32_16x16x32_bf16 v[56:59], v[142:145], v[192:195], v[56:59]
	v_mfma_f32_16x16x32_bf16 v[44:47], v[134:137], v[212:215], v[44:47]
	v_mfma_f32_16x16x32_bf16 v[40:43], v[142:145], v[212:215], v[40:43]
	v_mfma_f32_16x16x32_bf16 v[28:31], v[134:137], v[220:223], v[28:31]
	v_mfma_f32_16x16x32_bf16 v[24:27], v[142:145], v[220:223], v[24:27]
	v_mfma_f32_16x16x32_bf16 v[12:15], v[134:137], v[228:231], v[12:15]
	v_mfma_f32_16x16x32_bf16 v[8:11], v[142:145], v[228:231], v[8:11]
	v_mfma_f32_16x16x32_bf16 v[52:55], v[146:149], v[188:191], v[52:55]
	v_mfma_f32_16x16x32_bf16 v[48:51], v[154:157], v[188:191], v[48:51]
	v_mfma_f32_16x16x32_bf16 v[36:39], v[146:149], v[208:211], v[36:39]
	v_mfma_f32_16x16x32_bf16 v[32:35], v[154:157], v[208:211], v[32:35]
	v_mfma_f32_16x16x32_bf16 v[20:23], v[146:149], v[216:219], v[20:23]
	v_mfma_f32_16x16x32_bf16 v[16:19], v[154:157], v[216:219], v[16:19]
	v_mfma_f32_16x16x32_bf16 v[4:7], v[146:149], v[224:227], v[4:7]
	v_mfma_f32_16x16x32_bf16 v[0:3], v[154:157], v[224:227], v[0:3]
	v_mfma_f32_16x16x32_bf16 v[52:55], v[150:153], v[192:195], v[52:55]
	v_mfma_f32_16x16x32_bf16 v[48:51], v[158:161], v[192:195], v[48:51]
	v_mfma_f32_16x16x32_bf16 v[36:39], v[150:153], v[212:215], v[36:39]
	v_mfma_f32_16x16x32_bf16 v[32:35], v[158:161], v[212:215], v[32:35]
	v_mfma_f32_16x16x32_bf16 v[20:23], v[150:153], v[220:223], v[20:23]
	v_mfma_f32_16x16x32_bf16 v[16:19], v[158:161], v[220:223], v[16:19]
	v_mfma_f32_16x16x32_bf16 v[4:7], v[150:153], v[228:231], v[4:7]
	v_mfma_f32_16x16x32_bf16 v[0:3], v[158:161], v[228:231], v[0:3]
	s_waitcnt vmcnt(8)
	s_setprio 0
	s_barrier
; #define PG8_STAGE(bufoff, gbase, voff) do { _Pragma("unroll") for (int _i = 0; _i < 2; ++_i) \
;         __builtin_amdgcn_global_load_lds((const unsigned*)((const char*)(gbase) + (voff)[_i]), (PG8_LAS unsigned*)(lds + (bufoff) + ldsw + _i * 8192), 16, 0, 0); } while (0)
; #define PG8_LDA(dst, b, h) do { _Pragma("unroll") for (int m = 0; m < 4; ++m) _Pragma("unroll") for (int k = 0; k < 2; ++k) dst[m][k] = *(const PG8_LAS bf16x8*)(lds + PG8_SA(b, h) + aoff + m * 2048 + k * 1024); } while (0)
; #define PG8_LDB(dst, b, h) do { _Pragma("unroll") for (int n = 0; n < 2; ++n) _Pragma("unroll") for (int k = 0; k < 2; ++k) dst[n][k] = *(const PG8_LAS bf16x8*)(lds + PG8_SB(b, h) + boff + n * 2048 + k * 1024); } while (0)
; #define PG8_MMA(ai, bj, At, Bt) do { __builtin_amdgcn_s_setprio(1); _Pragma("unroll") for (int m = 0; m < 4; ++m) _Pragma("unroll") for (int n = 0; n < 2; ++n) _Pragma("unroll") for (int k = 0; k < 2; ++k) \
;         acc[ai][bj][m][n] = __builtin_amdgcn_mfma_f32_16x16x32_bf16(Bt[n][k], At[m][k], acc[ai][bj][m][n], 0, 0, 0); __builtin_amdgcn_s_setprio(0); } while (0)
; #define PG8_WAIT_V(n) asm volatile("s_waitcnt vmcnt(" #n ")" ::: "memory")
; #define PG8_WAIT_L(n) asm volatile("s_waitcnt lgkmcnt(" #n ")" ::: "memory")
; #define PG8_BAR __builtin_amdgcn_s_barrier()
; #define PG8_SCHED __builtin_amdgcn_sched_barrier(0)
; template <class Epi, class Sched, bool ALIGN_EPI = false, bool SP2 = false>
; __device__ __forceinline__ void gemm_phase(PG8_LAS unsigned char* lds, const Gemm g, const Sched& S, const Epi& E) {
;     ...
;             PG8_LDB(B0, 1, 0); PG8_LDB(B1, 1, 1); PG8_SCHED; PG8_LDA(At, 1, 0); PG8_STAGE(PG8_SA(0, 1), a2 + hstep, voffA);
;             PG8_WAIT_V(8); PG8_WAIT_L(0); PG8_BAR; PG8_MMA(0, 0, At, B0); PG8_MMA(0, 1, At, B1); PG8_BAR; PG8_SCHED;
	s_add_i32 s71, 0, 0x18000
	s_add_i32 s72, 0, 0x1c000
	v_add_u32_e32 v142, s71, v199
	v_add_u32_e32 v158, s72, v199
	ds_read_b128 v[130:133], v142
	ds_read_b128 v[134:137], v142 offset:1024
	ds_read_b128 v[138:141], v142 offset:2048
	ds_read_b128 v[142:145], v142 offset:3072
	ds_read_b128 v[146:149], v158
	ds_read_b128 v[150:153], v158 offset:1024
	ds_read_b128 v[154:157], v158 offset:2048
	ds_read_b128 v[158:161], v158 offset:3072
	s_add_u32 s50, s50, 0x40000
	s_addc_u32 s51, s51, 0
	s_mov_b32 m0, s56
	v_lshl_add_u64 v[238:239], s[50:51], 0, v[176:177]
	ds_read_b128 v[188:191], v200 offset:32768
	ds_read_b128 v[192:195], v200 offset:33792
	ds_read_b128 v[208:211], v200 offset:34816
	ds_read_b128 v[212:215], v200 offset:35840
	ds_read_b128 v[216:219], v200 offset:36864
	ds_read_b128 v[220:223], v200 offset:37888
	ds_read_b128 v[224:227], v200 offset:38912
	ds_read_b128 v[228:231], v200 offset:39936
	global_load_lds_dwordx4 v[238:239], off
	v_lshl_add_u64 v[238:239], s[50:51], 0, v[180:181]
	s_mov_b32 m0, s57
	s_nop 0
	global_load_lds_dwordx4 v[238:239], off
	s_waitcnt lgkmcnt(0)
	s_setprio 1
	s_barrier
	v_mfma_f32_16x16x32_bf16 v[126:129], v[130:133], v[188:191], v[126:129]
	v_mfma_f32_16x16x32_bf16 v[122:125], v[138:141], v[188:191], v[122:125]
	v_mfma_f32_16x16x32_bf16 v[110:113], v[130:133], v[208:211], v[110:113]
	v_mfma_f32_16x16x32_bf16 v[106:109], v[138:141], v[208:211], v[106:109]
	v_mfma_f32_16x16x32_bf16 v[94:97], v[130:133], v[216:219], v[94:97]
	v_mfma_f32_16x16x32_bf16 v[90:93], v[138:141], v[216:219], v[90:93]
	v_mfma_f32_16x16x32_bf16 v[76:79], v[130:133], v[224:227], v[76:79]
	v_mfma_f32_16x16x32_bf16 v[72:75], v[138:141], v[224:227], v[72:75]
	v_mfma_f32_16x16x32_bf16 v[126:129], v[134:137], v[192:195], v[126:129]
	v_mfma_f32_16x16x32_bf16 v[122:125], v[142:145], v[192:195], v[122:125]
	v_mfma_f32_16x16x32_bf16 v[110:113], v[134:137], v[212:215], v[110:113]
	v_mfma_f32_16x16x32_bf16 v[106:109], v[142:145], v[212:215], v[106:109]
	v_mfma_f32_16x16x32_bf16 v[94:97], v[134:137], v[220:223], v[94:97]
	v_mfma_f32_16x16x32_bf16 v[90:93], v[142:145], v[220:223], v[90:93]
	v_mfma_f32_16x16x32_bf16 v[76:79], v[134:137], v[228:231], v[76:79]
	v_mfma_f32_16x16x32_bf16 v[72:75], v[142:145], v[228:231], v[72:75]
	v_mfma_f32_16x16x32_bf16 v[118:121], v[146:149], v[188:191], v[118:121]
	v_mfma_f32_16x16x32_bf16 v[114:117], v[154:157], v[188:191], v[114:117]
	v_mfma_f32_16x16x32_bf16 v[102:105], v[146:149], v[208:211], v[102:105]
	v_mfma_f32_16x16x32_bf16 v[98:101], v[154:157], v[208:211], v[98:101]
	v_mfma_f32_16x16x32_bf16 v[86:89], v[146:149], v[216:219], v[86:89]
	v_mfma_f32_16x16x32_bf16 v[82:85], v[154:157], v[216:219], v[82:85]
	v_mfma_f32_16x16x32_bf16 v[68:71], v[146:149], v[224:227], v[68:71]
	v_mfma_f32_16x16x32_bf16 v[64:67], v[154:157], v[224:227], v[64:67]
	v_mfma_f32_16x16x32_bf16 v[118:121], v[150:153], v[192:195], v[118:121]
	v_mfma_f32_16x16x32_bf16 v[114:117], v[158:161], v[192:195], v[114:117]
	v_mfma_f32_16x16x32_bf16 v[102:105], v[150:153], v[212:215], v[102:105]
	v_mfma_f32_16x16x32_bf16 v[98:101], v[158:161], v[212:215], v[98:101]
	v_mfma_f32_16x16x32_bf16 v[86:89], v[150:153], v[220:223], v[86:89]
	v_mfma_f32_16x16x32_bf16 v[82:85], v[158:161], v[220:223], v[82:85]
	v_mfma_f32_16x16x32_bf16 v[68:71], v[150:153], v[228:231], v[68:71]
	v_mfma_f32_16x16x32_bf16 v[64:67], v[158:161], v[228:231], v[64:67]
	s_waitcnt vmcnt(8)
	s_setprio 0
	s_barrier
; #define PG8_STAGE(bufoff, gbase, voff) do { _Pragma("unroll") for (int _i = 0; _i < 2; ++_i) \
;         __builtin_amdgcn_global_load_lds((const unsigned*)((const char*)(gbase) + (voff)[_i]), (PG8_LAS unsigned*)(lds + (bufoff) + ldsw + _i * 8192), 16, 0, 0); } while (0)
; #define PG8_LDA(dst, b, h) do { _Pragma("unroll") for (int m = 0; m < 4; ++m) _Pragma("unroll") for (int k = 0; k < 2; ++k) dst[m][k] = *(const PG8_LAS bf16x8*)(lds + PG8_SA(b, h) + aoff + m * 2048 + k * 1024); } while (0)
; #define PG8_MMA(ai, bj, At, Bt) do { __builtin_amdgcn_s_setprio(1); _Pragma("unroll") for (int m = 0; m < 4; ++m) _Pragma("unroll") for (int n = 0; n < 2; ++n) _Pragma("unroll") for (int k = 0; k < 2; ++k) \
;         acc[ai][bj][m][n] = __builtin_amdgcn_mfma_f32_16x16x32_bf16(Bt[n][k], At[m][k], acc[ai][bj][m][n], 0, 0, 0); __builtin_amdgcn_s_setprio(0); } while (0)
; #define PG8_WAIT_V(n) asm volatile("s_waitcnt vmcnt(" #n ")" ::: "memory")
; #define PG8_WAIT_L(n) asm volatile("s_waitcnt lgkmcnt(" #n ")" ::: "memory")
; #define PG8_BAR __builtin_amdgcn_s_barrier()
; #define PG8_SCHED __builtin_amdgcn_sched_barrier(0)
; template <class Epi, class Sched, bool ALIGN_EPI = false, bool SP2 = false>
; __device__ __forceinline__ void gemm_phase(PG8_LAS unsigned char* lds, const Gemm g, const Sched& S, const Epi& E) {
;     ...
;         for (int t = 0; t < nt; t += 2) {
;     ...
;             PG8_LDA(At, 1, 1); PG8_STAGE(PG8_SB(1, 0), b3, voffB); PG8_STAGE(PG8_SB(1, 1), b3 + hstep, voffB); PG8_STAGE(PG8_SA(1, 0), a3, voffA);
;             PG8_WAIT_V(8); PG8_WAIT_L(0); PG8_BAR; PG8_MMA(1, 0, At, B0); PG8_MMA(1, 1, At, B1); PG8_BAR; PG8_SCHED;
	s_add_i32 s50, s71, s54
	v_lshl_add_u64 v[196:197], v[196:197], 0, s[40:41]
	s_mov_b32 m0, s50
	ds_read_b128 v[188:191], v200 offset:49152
	ds_read_b128 v[192:195], v200 offset:50176
	ds_read_b128 v[208:211], v200 offset:51200
	ds_read_b128 v[212:215], v200 offset:52224
	ds_read_b128 v[216:219], v200 offset:53248
	ds_read_b128 v[220:223], v200 offset:54272
	ds_read_b128 v[224:227], v200 offset:55296
	ds_read_b128 v[228:231], v200 offset:56320
	global_load_lds_dwordx4 v[196:197], off
	s_add_i32 m0, s50, 0x2000
	s_add_u32 s48, s48, 0x40080
	v_lshl_add_u64 v[196:197], v[232:233], 0, s[40:41]
	s_addc_u32 s49, s49, 0
	s_add_i32 s50, s72, s54
	global_load_lds_dwordx4 v[196:197], off
	v_lshl_add_u64 v[196:197], s[48:49], 0, v[178:179]
	s_mov_b32 m0, s50
	s_nop 0
	global_load_lds_dwordx4 v[196:197], off
	v_lshl_add_u64 v[196:197], s[48:49], 0, v[182:183]
	s_add_i32 m0, s50, 0x2000
	s_nop 0
	global_load_lds_dwordx4 v[196:197], off
	v_lshl_add_u64 v[196:197], v[234:235], 0, s[40:41]
	s_mov_b32 m0, s61
	s_nop 0
	global_load_lds_dwordx4 v[196:197], off
	v_lshl_add_u64 v[196:197], v[236:237], 0, s[40:41]
	s_mov_b32 m0, s62
	s_nop 0
	global_load_lds_dwordx4 v[196:197], off
	s_waitcnt lgkmcnt(0)
	s_setprio 1
	s_barrier
	v_mfma_f32_16x16x32_bf16 v[60:63], v[130:133], v[188:191], v[60:63]
	v_mfma_f32_16x16x32_bf16 v[56:59], v[138:141], v[188:191], v[56:59]
	v_mfma_f32_16x16x32_bf16 v[44:47], v[130:133], v[208:211], v[44:47]
	v_mfma_f32_16x16x32_bf16 v[40:43], v[138:141], v[208:211], v[40:43]
	v_mfma_f32_16x16x32_bf16 v[28:31], v[130:133], v[216:219], v[28:31]
	v_mfma_f32_16x16x32_bf16 v[24:27], v[138:141], v[216:219], v[24:27]
	v_mfma_f32_16x16x32_bf16 v[12:15], v[130:133], v[224:227], v[12:15]
	v_mfma_f32_16x16x32_bf16 v[8:11], v[138:141], v[224:227], v[8:11]
	v_mfma_f32_16x16x32_bf16 v[60:63], v[134:137], v[192:195], v[60:63]
	v_mfma_f32_16x16x32_bf16 v[56:59], v[142:145], v[192:195], v[56:59]
	v_mfma_f32_16x16x32_bf16 v[44:47], v[134:137], v[212:215], v[44:47]
	v_mfma_f32_16x16x32_bf16 v[40:43], v[142:145], v[212:215], v[40:43]
	v_mfma_f32_16x16x32_bf16 v[28:31], v[134:137], v[220:223], v[28:31]
	v_mfma_f32_16x16x32_bf16 v[24:27], v[142:145], v[220:223], v[24:27]
	v_mfma_f32_16x16x32_bf16 v[12:15], v[134:137], v[228:231], v[12:15]
	v_mfma_f32_16x16x32_bf16 v[8:11], v[142:145], v[228:231], v[8:11]
	v_mfma_f32_16x16x32_bf16 v[52:55], v[146:149], v[188:191], v[52:55]
	v_mfma_f32_16x16x32_bf16 v[48:51], v[154:157], v[188:191], v[48:51]
	v_mfma_f32_16x16x32_bf16 v[36:39], v[146:149], v[208:211], v[36:39]
	v_mfma_f32_16x16x32_bf16 v[32:35], v[154:157], v[208:211], v[32:35]
	v_mfma_f32_16x16x32_bf16 v[20:23], v[146:149], v[216:219], v[20:23]
	v_mfma_f32_16x16x32_bf16 v[16:19], v[154:157], v[216:219], v[16:19]
	v_mfma_f32_16x16x32_bf16 v[4:7], v[146:149], v[224:227], v[4:7]
	v_mfma_f32_16x16x32_bf16 v[0:3], v[154:157], v[224:227], v[0:3]
	v_mfma_f32_16x16x32_bf16 v[52:55], v[150:153], v[192:195], v[52:55]
	v_mfma_f32_16x16x32_bf16 v[48:51], v[158:161], v[192:195], v[48:51]
	v_mfma_f32_16x16x32_bf16 v[36:39], v[150:153], v[212:215], v[36:39]
	v_mfma_f32_16x16x32_bf16 v[32:35], v[158:161], v[212:215], v[32:35]
	v_mfma_f32_16x16x32_bf16 v[20:23], v[150:153], v[220:223], v[20:23]
	v_mfma_f32_16x16x32_bf16 v[16:19], v[158:161], v[220:223], v[16:19]
	v_mfma_f32_16x16x32_bf16 v[4:7], v[150:153], v[228:231], v[4:7]
	v_mfma_f32_16x16x32_bf16 v[0:3], v[158:161], v[228:231], v[0:3]
	s_waitcnt vmcnt(8)
	s_setprio 0
	s_barrier
	s_add_i32 s70, s70, 2
	s_add_u32 s6, s6, 0x100
	s_addc_u32 s7, s7, 0
	s_add_u32 s68, s68, 0x100
	s_addc_u32 s69, s69, 0
	s_cmp_gt_u32 s70, 13
	s_cbranch_scc0 .Lqkv_A
	s_branch .Lqkv_done

; template <class Epi, class Sched, bool ALIGN_EPI = false, bool SP2 = false>
; __device__ __forceinline__ void gemm_phase(PG8_LAS unsigned char* lds, const Gemm g, const Sched& S, const Epi& E) {
;     ...
;     f32x4 acc[2][2][4][2];
; #pragma unroll
;     for (int a = 0; a < 2; ++a)
; #pragma unroll
;         for (int b = 0; b < 2; ++b)
; #pragma unroll
;             for (int m = 0; m < 4; ++m)
; #pragma unroll
;                 for (int n = 0; n < 2; ++n) acc[a][b][m][n] = (f32x4){0.f, 0.f, 0.f, 0.f};
;     __device__ __forceinline__ void prefetch(const Unit& u, int tid, PG8_LAS unsigned char* scratch) const {
;         const bf16_t* sb = xb + ((size_t)(u.pm * BM) * 1024 + u.pn * BM);
;         const unsigned voff = (unsigned)(((tid >> 2) * 1024 + (tid & 3) * 64) * 2);
;         const unsigned l0 = (unsigned)__builtin_amdgcn_readfirstlane((int)(unsigned)(uintptr_t)scratch);
;         const bf16_t* sb2 = sb + (size_t)128 * 1024;
.LBB0_382:
	s_lshl_b32 s46, s46, 8
	s_ashr_i32 s47, s46, 31
	s_lshl_b32 s48, s20, 8
	s_ashr_i32 s49, s48, 31
	s_lshl_b64 s[50:51], s[46:47], 11
	s_add_u32 s47, s30, s50
	s_addc_u32 s52, s31, s51
	s_lshl_b64 s[50:51], s[48:49], 1
	s_add_u32 s50, s47, s50
	s_addc_u32 s51, s52, s51
	s_add_u32 s52, s50, 0x40000
	s_addc_u32 s53, s51, 0
	s_add_u32 s47, s54, 0x100
	s_addc_u32 s49, s55, 0
	s_add_u32 s54, s44, 0x80
	s_addc_u32 s55, s45, 0
	v_mov_b32_e32 v0, 0
	v_lshl_add_u64 v[130:131], s[54:55], 0, v[180:181]
	v_lshl_add_u64 v[132:133], s[54:55], 0, v[182:183]
	s_mov_b32 s56, 0
	s_mov_b64 s[54:55], 0
	s_waitcnt lgkmcnt(0)
	v_mov_b32_e32 v1, v0
	v_mov_b32_e32 v2, v0
	v_mov_b32_e32 v3, v0
	v_mov_b32_e32 v4, v0
	v_mov_b32_e32 v5, v0
	v_mov_b32_e32 v6, v0
	v_mov_b32_e32 v7, v0
	v_mov_b32_e32 v16, v0
	v_mov_b32_e32 v17, v0
	v_mov_b32_e32 v18, v0
	v_mov_b32_e32 v19, v0
	v_mov_b32_e32 v20, v0
	v_mov_b32_e32 v21, v0
	v_mov_b32_e32 v22, v0
	v_mov_b32_e32 v23, v0
	v_mov_b32_e32 v32, v0
	v_mov_b32_e32 v33, v0
	v_mov_b32_e32 v34, v0
	v_mov_b32_e32 v35, v0
	v_mov_b32_e32 v36, v0
	v_mov_b32_e32 v37, v0
	v_mov_b32_e32 v38, v0
	v_mov_b32_e32 v39, v0
	v_mov_b32_e32 v48, v0
	v_mov_b32_e32 v49, v0
	v_mov_b32_e32 v50, v0
	v_mov_b32_e32 v51, v0
	v_mov_b32_e32 v52, v0
	v_mov_b32_e32 v53, v0
	v_mov_b32_e32 v54, v0
	v_mov_b32_e32 v55, v0
	v_mov_b32_e32 v8, v0
	v_mov_b32_e32 v9, v0
	v_mov_b32_e32 v10, v0
	v_mov_b32_e32 v11, v0
	v_mov_b32_e32 v12, v0
	v_mov_b32_e32 v13, v0
	v_mov_b32_e32 v14, v0
	v_mov_b32_e32 v15, v0
	v_mov_b32_e32 v24, v0
	v_mov_b32_e32 v25, v0
	v_mov_b32_e32 v26, v0
	v_mov_b32_e32 v27, v0
	v_mov_b32_e32 v28, v0
	v_mov_b32_e32 v29, v0
	v_mov_b32_e32 v30, v0
	v_mov_b32_e32 v31, v0
	v_mov_b32_e32 v40, v0
	v_mov_b32_e32 v41, v0
	v_mov_b32_e32 v42, v0
	v_mov_b32_e32 v43, v0
	v_mov_b32_e32 v44, v0
	v_mov_b32_e32 v45, v0
	v_mov_b32_e32 v46, v0
	v_mov_b32_e32 v47, v0
	v_mov_b32_e32 v56, v0
	v_mov_b32_e32 v57, v0
	v_mov_b32_e32 v58, v0
	v_mov_b32_e32 v59, v0
	v_mov_b32_e32 v60, v0
	v_mov_b32_e32 v61, v0
	v_mov_b32_e32 v62, v0
	v_mov_b32_e32 v63, v0
	v_mov_b32_e32 v64, v0
	v_mov_b32_e32 v65, v0
	v_mov_b32_e32 v66, v0
	v_mov_b32_e32 v67, v0
	v_mov_b32_e32 v68, v0
	v_mov_b32_e32 v69, v0
	v_mov_b32_e32 v70, v0
	v_mov_b32_e32 v71, v0
	v_mov_b32_e32 v82, v0
	v_mov_b32_e32 v83, v0
	v_mov_b32_e32 v84, v0
	v_mov_b32_e32 v85, v0
	v_mov_b32_e32 v86, v0
	v_mov_b32_e32 v87, v0
	v_mov_b32_e32 v88, v0
	v_mov_b32_e32 v89, v0
	v_mov_b32_e32 v98, v0
	v_mov_b32_e32 v99, v0
	v_mov_b32_e32 v100, v0
	v_mov_b32_e32 v101, v0
	v_mov_b32_e32 v102, v0
	v_mov_b32_e32 v103, v0
	v_mov_b32_e32 v104, v0
	v_mov_b32_e32 v105, v0
	v_mov_b32_e32 v114, v0
	v_mov_b32_e32 v115, v0
	v_mov_b32_e32 v116, v0
	v_mov_b32_e32 v117, v0
	v_mov_b32_e32 v118, v0
	v_mov_b32_e32 v119, v0
	v_mov_b32_e32 v120, v0
	v_mov_b32_e32 v121, v0
	v_mov_b32_e32 v72, v0
	v_mov_b32_e32 v73, v0
	v_mov_b32_e32 v74, v0
	v_mov_b32_e32 v75, v0
	v_mov_b32_e32 v76, v0
	v_mov_b32_e32 v77, v0
	v_mov_b32_e32 v78, v0
	v_mov_b32_e32 v79, v0
	v_mov_b32_e32 v90, v0
	v_mov_b32_e32 v91, v0
	v_mov_b32_e32 v92, v0
	v_mov_b32_e32 v93, v0
	v_mov_b32_e32 v94, v0
	v_mov_b32_e32 v95, v0
	v_mov_b32_e32 v96, v0
	v_mov_b32_e32 v97, v0
	v_mov_b32_e32 v106, v0
	v_mov_b32_e32 v107, v0
	v_mov_b32_e32 v108, v0
	v_mov_b32_e32 v109, v0
	v_mov_b32_e32 v110, v0
	v_mov_b32_e32 v111, v0
	v_mov_b32_e32 v112, v0
	v_mov_b32_e32 v113, v0
	v_mov_b32_e32 v122, v0
	v_mov_b32_e32 v123, v0
	v_mov_b32_e32 v124, v0
	v_mov_b32_e32 v125, v0
	v_mov_b32_e32 v126, v0
	v_mov_b32_e32 v127, v0
	v_mov_b32_e32 v128, v0
	v_mov_b32_e32 v129, v0
	v_readfirstlane_b32 s100, v202
	s_nop 3
	s_lshr_b32 s100, s100, 8
	s_cmp_eq_u32 s100, 0
	s_cbranch_scc0 .LBB0_384
	s_branch .Lop_A384

; #define PG8_STAGE(bufoff, gbase, voff) do { _Pragma("unroll") for (int _i = 0; _i < 2; ++_i) \
;         __builtin_amdgcn_global_load_lds((const unsigned*)((const char*)(gbase) + (voff)[_i]), (PG8_LAS unsigned*)(lds + (bufoff) + ldsw + _i * 8192), 16, 0, 0); } while (0)
; #define PG8_LDA(dst, b, h) do { _Pragma("unroll") for (int m = 0; m < 4; ++m) _Pragma("unroll") for (int k = 0; k < 2; ++k) dst[m][k] = *(const PG8_LAS bf16x8*)(lds + PG8_SA(b, h) + aoff + m * 2048 + k * 1024); } while (0)
; #define PG8_LDB(dst, b, h) do { _Pragma("unroll") for (int n = 0; n < 2; ++n) _Pragma("unroll") for (int k = 0; k < 2; ++k) dst[n][k] = *(const PG8_LAS bf16x8*)(lds + PG8_SB(b, h) + boff + n * 2048 + k * 1024); } while (0)
; #define PG8_MMA(ai, bj, At, Bt) do { __builtin_amdgcn_s_setprio(1); _Pragma("unroll") for (int m = 0; m < 4; ++m) _Pragma("unroll") for (int n = 0; n < 2; ++n) _Pragma("unroll") for (int k = 0; k < 2; ++k) \
;         acc[ai][bj][m][n] = __builtin_amdgcn_mfma_f32_16x16x32_bf16(Bt[n][k], At[m][k], acc[ai][bj][m][n], 0, 0, 0); __builtin_amdgcn_s_setprio(0); } while (0)
; #define PG8_WAIT_V(n) asm volatile("s_waitcnt vmcnt(" #n ")" ::: "memory")
; #define PG8_WAIT_L(n) asm volatile("s_waitcnt lgkmcnt(" #n ")" ::: "memory")
; #define PG8_BAR __builtin_amdgcn_s_barrier()
; #define PG8_SCHED __builtin_amdgcn_sched_barrier(0)
; template <class Epi, class Sched, bool ALIGN_EPI = false, bool SP2 = false>
; __device__ __forceinline__ void gemm_phase(PG8_LAS unsigned char* lds, const Gemm g, const Sched& S, const Epi& E) {
;     ...
;             PG8_LDB(B0, 0, 0); PG8_LDB(B1, 0, 1); PG8_SCHED; PG8_LDA(At, 0, 0); PG8_STAGE(PG8_SA(1, 1), a1 + hstep, voffA);
;             PG8_WAIT_V(8); PG8_WAIT_L(0); PG8_BAR; PG8_MMA(0, 0, At, B0); PG8_MMA(0, 1, At, B1); PG8_BAR; PG8_SCHED;
;             PG8_LDA(At, 0, 1); PG8_STAGE(PG8_SB(0, 0), b2, voffB); PG8_STAGE(PG8_SB(0, 1), b2 + hstep, voffB); PG8_STAGE(PG8_SA(0, 0), a2, voffA);
;             PG8_WAIT_V(8); PG8_WAIT_L(0); PG8_BAR; PG8_MMA(1, 0, At, B0); PG8_MMA(1, 1, At, B1); PG8_BAR; PG8_SCHED;
.Lop_A383:
	s_add_i32 s73, s56, 2
	s_add_u32 s57, s44, s54
	s_addc_u32 s74, s45, s55
	s_add_u32 s75, s57, 0x100
	s_addc_u32 s57, s74, 0
	s_add_u32 s74, s47, s54
	s_addc_u32 s76, s49, s55
	s_add_i32 s77, 0, 0x10000
	s_cmp_eq_u32 s15, s56
	s_cselect_b32 s57, s5, s57
	s_cselect_b32 s56, s4, s75
	s_cselect_b32 s75, s43, s76
	s_cselect_b32 s74, s42, s74
	s_add_i32 s76, 0, 0x14000
	v_add_u32_e32 v146, s77, v209
	v_add_u32_e32 v188, s76, v209
	ds_read_b128 v[134:137], v146
	ds_read_b128 v[138:141], v146 offset:1024
	ds_read_b128 v[142:145], v146 offset:2048
	ds_read_b128 v[146:149], v146 offset:3072
	ds_read_b128 v[150:153], v188
	ds_read_b128 v[154:157], v188 offset:1024
	ds_read_b128 v[184:187], v188 offset:2048
	ds_read_b128 v[188:191], v188 offset:3072
	v_lshl_add_u64 v[200:201], v[130:131], 0, s[54:55]
	s_add_i32 m0, s58, 0xc000
	ds_read_b128 v[192:195], v211
	ds_read_b128 v[196:199], v211 offset:1024
	ds_read_b128 v[212:215], v211 offset:2048
	ds_read_b128 v[216:219], v211 offset:3072
	ds_read_b128 v[220:223], v211 offset:4096
	ds_read_b128 v[224:227], v211 offset:5120
	ds_read_b128 v[228:231], v211 offset:6144
	ds_read_b128 v[232:235], v211 offset:7168
	global_load_lds_dwordx4 v[200:201], off
	v_lshl_add_u64 v[200:201], v[132:133], 0, s[54:55]
	s_add_i32 m0, s58, 0xe000
	s_nop 0
	global_load_lds_dwordx4 v[200:201], off
	s_waitcnt lgkmcnt(0)
	s_setprio 1
	s_barrier
	v_mfma_f32_16x16x32_bf16 v[126:129], v[134:137], v[192:195], v[126:129]
	v_mfma_f32_16x16x32_bf16 v[122:125], v[142:145], v[192:195], v[122:125]
	v_mfma_f32_16x16x32_bf16 v[110:113], v[134:137], v[212:215], v[110:113]
	v_mfma_f32_16x16x32_bf16 v[106:109], v[142:145], v[212:215], v[106:109]
	v_mfma_f32_16x16x32_bf16 v[94:97], v[134:137], v[220:223], v[94:97]
	v_mfma_f32_16x16x32_bf16 v[90:93], v[142:145], v[220:223], v[90:93]
	v_mfma_f32_16x16x32_bf16 v[76:79], v[134:137], v[228:231], v[76:79]
	v_mfma_f32_16x16x32_bf16 v[72:75], v[142:145], v[228:231], v[72:75]
	v_mfma_f32_16x16x32_bf16 v[126:129], v[138:141], v[196:199], v[126:129]
	v_mfma_f32_16x16x32_bf16 v[122:125], v[146:149], v[196:199], v[122:125]
	v_mfma_f32_16x16x32_bf16 v[110:113], v[138:141], v[216:219], v[110:113]
	v_mfma_f32_16x16x32_bf16 v[106:109], v[146:149], v[216:219], v[106:109]
	v_mfma_f32_16x16x32_bf16 v[94:97], v[138:141], v[224:227], v[94:97]
	v_mfma_f32_16x16x32_bf16 v[90:93], v[146:149], v[224:227], v[90:93]
	v_mfma_f32_16x16x32_bf16 v[76:79], v[138:141], v[232:235], v[76:79]
	v_mfma_f32_16x16x32_bf16 v[72:75], v[146:149], v[232:235], v[72:75]
	v_mfma_f32_16x16x32_bf16 v[118:121], v[150:153], v[192:195], v[118:121]
	v_mfma_f32_16x16x32_bf16 v[114:117], v[184:187], v[192:195], v[114:117]
	v_mfma_f32_16x16x32_bf16 v[102:105], v[150:153], v[212:215], v[102:105]
	v_mfma_f32_16x16x32_bf16 v[98:101], v[184:187], v[212:215], v[98:101]
	v_mfma_f32_16x16x32_bf16 v[86:89], v[150:153], v[220:223], v[86:89]
	v_mfma_f32_16x16x32_bf16 v[82:85], v[184:187], v[220:223], v[82:85]
	v_mfma_f32_16x16x32_bf16 v[68:71], v[150:153], v[228:231], v[68:71]
	v_mfma_f32_16x16x32_bf16 v[64:67], v[184:187], v[228:231], v[64:67]
	v_mfma_f32_16x16x32_bf16 v[118:121], v[154:157], v[196:199], v[118:121]
	v_mfma_f32_16x16x32_bf16 v[114:117], v[188:191], v[196:199], v[114:117]
	v_mfma_f32_16x16x32_bf16 v[102:105], v[154:157], v[216:219], v[102:105]
	v_mfma_f32_16x16x32_bf16 v[98:101], v[188:191], v[216:219], v[98:101]
	v_mfma_f32_16x16x32_bf16 v[86:89], v[154:157], v[224:227], v[86:89]
	v_mfma_f32_16x16x32_bf16 v[82:85], v[188:191], v[224:227], v[82:85]
	v_mfma_f32_16x16x32_bf16 v[68:71], v[154:157], v[232:235], v[68:71]
	v_mfma_f32_16x16x32_bf16 v[64:67], v[188:191], v[232:235], v[64:67]
	s_waitcnt vmcnt(8)
	s_setprio 0
	s_barrier
	s_add_i32 s77, s77, s39
	v_lshl_add_u64 v[200:201], s[74:75], 0, v[176:177]
	s_mov_b32 m0, s77
	ds_read_b128 v[192:195], v211 offset:16384
	ds_read_b128 v[196:199], v211 offset:17408
	ds_read_b128 v[212:215], v211 offset:18432
	ds_read_b128 v[216:219], v211 offset:19456
	ds_read_b128 v[220:223], v211 offset:20480
	ds_read_b128 v[224:227], v211 offset:21504
	ds_read_b128 v[228:231], v211 offset:22528
	ds_read_b128 v[232:235], v211 offset:23552
	global_load_lds_dwordx4 v[200:201], off
	s_add_i32 m0, s77, 0x2000
	v_lshl_add_u64 v[236:237], s[74:75], 0, v[158:159]
	s_add_u32 s74, s74, s14
	s_addc_u32 s75, s75, 0
	s_add_i32 s76, s76, s39
	global_load_lds_dwordx4 v[236:237], off
	v_lshl_add_u64 v[238:239], s[74:75], 0, v[176:177]
	s_mov_b32 m0, s76
	v_lshl_add_u64 v[240:241], s[74:75], 0, v[158:159]
	global_load_lds_dwordx4 v[238:239], off
	s_add_i32 m0, s76, 0x2000
	v_lshl_add_u64 v[242:243], s[56:57], 0, v[178:179]
	global_load_lds_dwordx4 v[240:241], off
	s_mov_b32 m0, s58
	v_lshl_add_u64 v[244:245], s[56:57], 0, v[160:161]
	global_load_lds_dwordx4 v[242:243], off
	s_mov_b32 m0, s59
	s_nop 0
	global_load_lds_dwordx4 v[244:245], off
	s_waitcnt lgkmcnt(0)
	s_setprio 1
	s_barrier
; #define PG8_STAGE(bufoff, gbase, voff) do { _Pragma("unroll") for (int _i = 0; _i < 2; ++_i) \
;         __builtin_amdgcn_global_load_lds((const unsigned*)((const char*)(gbase) + (voff)[_i]), (PG8_LAS unsigned*)(lds + (bufoff) + ldsw + _i * 8192), 16, 0, 0); } while (0)
; #define PG8_LDA(dst, b, h) do { _Pragma("unroll") for (int m = 0; m < 4; ++m) _Pragma("unroll") for (int k = 0; k < 2; ++k) dst[m][k] = *(const PG8_LAS bf16x8*)(lds + PG8_SA(b, h) + aoff + m * 2048 + k * 1024); } while (0)
; #define PG8_LDB(dst, b, h) do { _Pragma("unroll") for (int n = 0; n < 2; ++n) _Pragma("unroll") for (int k = 0; k < 2; ++k) dst[n][k] = *(const PG8_LAS bf16x8*)(lds + PG8_SB(b, h) + boff + n * 2048 + k * 1024); } while (0)
; #define PG8_MMA(ai, bj, At, Bt) do { __builtin_amdgcn_s_setprio(1); _Pragma("unroll") for (int m = 0; m < 4; ++m) _Pragma("unroll") for (int n = 0; n < 2; ++n) _Pragma("unroll") for (int k = 0; k < 2; ++k) \
;         acc[ai][bj][m][n] = __builtin_amdgcn_mfma_f32_16x16x32_bf16(Bt[n][k], At[m][k], acc[ai][bj][m][n], 0, 0, 0); __builtin_amdgcn_s_setprio(0); } while (0)
; #define PG8_WAIT_V(n) asm volatile("s_waitcnt vmcnt(" #n ")" ::: "memory")
; #define PG8_WAIT_L(n) asm volatile("s_waitcnt lgkmcnt(" #n ")" ::: "memory")
; #define PG8_BAR __builtin_amdgcn_s_barrier()
; #define PG8_SCHED __builtin_amdgcn_sched_barrier(0)
; template <class Epi, class Sched, bool ALIGN_EPI = false, bool SP2 = false>
; __device__ __forceinline__ void gemm_phase(PG8_LAS unsigned char* lds, const Gemm g, const Sched& S, const Epi& E) {
;     ...
;             PG8_WAIT_V(8); PG8_WAIT_L(0); PG8_BAR; PG8_MMA(1, 0, At, B0); PG8_MMA(1, 1, At, B1); PG8_BAR; PG8_SCHED;
;             PG8_LDB(B0, 1, 0); PG8_LDB(B1, 1, 1); PG8_SCHED; PG8_LDA(At, 1, 0); PG8_STAGE(PG8_SA(0, 1), a2 + hstep, voffA);
;             PG8_WAIT_V(8); PG8_WAIT_L(0); PG8_BAR; PG8_MMA(0, 0, At, B0); PG8_MMA(0, 1, At, B1); PG8_BAR; PG8_SCHED;
	v_mfma_f32_16x16x32_bf16 v[60:63], v[134:137], v[192:195], v[60:63]
	v_mfma_f32_16x16x32_bf16 v[56:59], v[142:145], v[192:195], v[56:59]
	v_mfma_f32_16x16x32_bf16 v[44:47], v[134:137], v[212:215], v[44:47]
	v_mfma_f32_16x16x32_bf16 v[40:43], v[142:145], v[212:215], v[40:43]
	v_mfma_f32_16x16x32_bf16 v[28:31], v[134:137], v[220:223], v[28:31]
	v_mfma_f32_16x16x32_bf16 v[24:27], v[142:145], v[220:223], v[24:27]
	v_mfma_f32_16x16x32_bf16 v[12:15], v[134:137], v[228:231], v[12:15]
	v_mfma_f32_16x16x32_bf16 v[8:11], v[142:145], v[228:231], v[8:11]
	v_mfma_f32_16x16x32_bf16 v[60:63], v[138:141], v[196:199], v[60:63]
	v_mfma_f32_16x16x32_bf16 v[56:59], v[146:149], v[196:199], v[56:59]
	v_mfma_f32_16x16x32_bf16 v[44:47], v[138:141], v[216:219], v[44:47]
	v_mfma_f32_16x16x32_bf16 v[40:43], v[146:149], v[216:219], v[40:43]
	v_mfma_f32_16x16x32_bf16 v[28:31], v[138:141], v[224:227], v[28:31]
	v_mfma_f32_16x16x32_bf16 v[24:27], v[146:149], v[224:227], v[24:27]
	v_mfma_f32_16x16x32_bf16 v[12:15], v[138:141], v[232:235], v[12:15]
	v_mfma_f32_16x16x32_bf16 v[8:11], v[146:149], v[232:235], v[8:11]
	v_mfma_f32_16x16x32_bf16 v[52:55], v[150:153], v[192:195], v[52:55]
	v_mfma_f32_16x16x32_bf16 v[48:51], v[184:187], v[192:195], v[48:51]
	v_mfma_f32_16x16x32_bf16 v[36:39], v[150:153], v[212:215], v[36:39]
	v_mfma_f32_16x16x32_bf16 v[32:35], v[184:187], v[212:215], v[32:35]
	v_mfma_f32_16x16x32_bf16 v[20:23], v[150:153], v[220:223], v[20:23]
	v_mfma_f32_16x16x32_bf16 v[16:19], v[184:187], v[220:223], v[16:19]
	v_mfma_f32_16x16x32_bf16 v[4:7], v[150:153], v[228:231], v[4:7]
	v_mfma_f32_16x16x32_bf16 v[0:3], v[184:187], v[228:231], v[0:3]
	v_mfma_f32_16x16x32_bf16 v[52:55], v[154:157], v[196:199], v[52:55]
	v_mfma_f32_16x16x32_bf16 v[48:51], v[188:191], v[196:199], v[48:51]
	v_mfma_f32_16x16x32_bf16 v[36:39], v[154:157], v[216:219], v[36:39]
	v_mfma_f32_16x16x32_bf16 v[32:35], v[188:191], v[216:219], v[32:35]
	v_mfma_f32_16x16x32_bf16 v[20:23], v[154:157], v[224:227], v[20:23]
	v_mfma_f32_16x16x32_bf16 v[16:19], v[188:191], v[224:227], v[16:19]
	v_mfma_f32_16x16x32_bf16 v[4:7], v[154:157], v[232:235], v[4:7]
	v_mfma_f32_16x16x32_bf16 v[0:3], v[188:191], v[232:235], v[0:3]
	s_waitcnt vmcnt(8)
	s_setprio 0
	s_barrier
	s_add_i32 s74, 0, 0x18000
	s_add_i32 s75, 0, 0x1c000
	v_add_u32_e32 v146, s74, v209
	v_add_u32_e32 v188, s75, v209
	ds_read_b128 v[134:137], v146
	ds_read_b128 v[138:141], v146 offset:1024
	ds_read_b128 v[142:145], v146 offset:2048
	ds_read_b128 v[146:149], v146 offset:3072
	ds_read_b128 v[150:153], v188
	ds_read_b128 v[154:157], v188 offset:1024
	ds_read_b128 v[184:187], v188 offset:2048
	ds_read_b128 v[188:191], v188 offset:3072
	s_add_u32 s56, s56, s14
	s_addc_u32 s57, s57, 0
	s_mov_b32 m0, s60
	v_lshl_add_u64 v[246:247], s[56:57], 0, v[178:179]
	ds_read_b128 v[192:195], v211 offset:32768
	ds_read_b128 v[196:199], v211 offset:33792
	ds_read_b128 v[212:215], v211 offset:34816
	ds_read_b128 v[216:219], v211 offset:35840
	ds_read_b128 v[220:223], v211 offset:36864
	ds_read_b128 v[224:227], v211 offset:37888
	ds_read_b128 v[228:231], v211 offset:38912
	ds_read_b128 v[232:235], v211 offset:39936
	global_load_lds_dwordx4 v[246:247], off
	v_lshl_add_u64 v[246:247], s[56:57], 0, v[160:161]
	s_mov_b32 m0, s61
	s_nop 0
	global_load_lds_dwordx4 v[246:247], off
	s_waitcnt lgkmcnt(0)
	s_setprio 1
	s_barrier
	v_mfma_f32_16x16x32_bf16 v[126:129], v[134:137], v[192:195], v[126:129]
	v_mfma_f32_16x16x32_bf16 v[122:125], v[142:145], v[192:195], v[122:125]
	v_mfma_f32_16x16x32_bf16 v[110:113], v[134:137], v[212:215], v[110:113]
	v_mfma_f32_16x16x32_bf16 v[106:109], v[142:145], v[212:215], v[106:109]
	v_mfma_f32_16x16x32_bf16 v[94:97], v[134:137], v[220:223], v[94:97]
	v_mfma_f32_16x16x32_bf16 v[90:93], v[142:145], v[220:223], v[90:93]
	v_mfma_f32_16x16x32_bf16 v[76:79], v[134:137], v[228:231], v[76:79]
	v_mfma_f32_16x16x32_bf16 v[72:75], v[142:145], v[228:231], v[72:75]
	v_mfma_f32_16x16x32_bf16 v[126:129], v[138:141], v[196:199], v[126:129]
	v_mfma_f32_16x16x32_bf16 v[122:125], v[146:149], v[196:199], v[122:125]
	v_mfma_f32_16x16x32_bf16 v[110:113], v[138:141], v[216:219], v[110:113]
	v_mfma_f32_16x16x32_bf16 v[106:109], v[146:149], v[216:219], v[106:109]
	v_mfma_f32_16x16x32_bf16 v[94:97], v[138:141], v[224:227], v[94:97]
	v_mfma_f32_16x16x32_bf16 v[90:93], v[146:149], v[224:227], v[90:93]
	v_mfma_f32_16x16x32_bf16 v[76:79], v[138:141], v[232:235], v[76:79]
	v_mfma_f32_16x16x32_bf16 v[72:75], v[146:149], v[232:235], v[72:75]
	v_mfma_f32_16x16x32_bf16 v[118:121], v[150:153], v[192:195], v[118:121]
	v_mfma_f32_16x16x32_bf16 v[114:117], v[184:187], v[192:195], v[114:117]
	v_mfma_f32_16x16x32_bf16 v[102:105], v[150:153], v[212:215], v[102:105]
	v_mfma_f32_16x16x32_bf16 v[98:101], v[184:187], v[212:215], v[98:101]
	v_mfma_f32_16x16x32_bf16 v[86:89], v[150:153], v[220:223], v[86:89]
	v_mfma_f32_16x16x32_bf16 v[82:85], v[184:187], v[220:223], v[82:85]
	v_mfma_f32_16x16x32_bf16 v[68:71], v[150:153], v[228:231], v[68:71]
	v_mfma_f32_16x16x32_bf16 v[64:67], v[184:187], v[228:231], v[64:67]
	v_mfma_f32_16x16x32_bf16 v[118:121], v[154:157], v[196:199], v[118:121]
	v_mfma_f32_16x16x32_bf16 v[114:117], v[188:191], v[196:199], v[114:117]
	v_mfma_f32_16x16x32_bf16 v[102:105], v[154:157], v[216:219], v[102:105]
	v_mfma_f32_16x16x32_bf16 v[98:101], v[188:191], v[216:219], v[98:101]
	v_mfma_f32_16x16x32_bf16 v[86:89], v[154:157], v[224:227], v[86:89]
	v_mfma_f32_16x16x32_bf16 v[82:85], v[188:191], v[224:227], v[82:85]
	v_mfma_f32_16x16x32_bf16 v[68:71], v[154:157], v[232:235], v[68:71]
	v_mfma_f32_16x16x32_bf16 v[64:67], v[188:191], v[232:235], v[64:67]
	s_waitcnt vmcnt(8)
	s_setprio 0
	s_barrier
; #define PG8_STAGE(bufoff, gbase, voff) do { _Pragma("unroll") for (int _i = 0; _i < 2; ++_i) \
;         __builtin_amdgcn_global_load_lds((const unsigned*)((const char*)(gbase) + (voff)[_i]), (PG8_LAS unsigned*)(lds + (bufoff) + ldsw + _i * 8192), 16, 0, 0); } while (0)
; #define PG8_LDA(dst, b, h) do { _Pragma("unroll") for (int m = 0; m < 4; ++m) _Pragma("unroll") for (int k = 0; k < 2; ++k) dst[m][k] = *(const PG8_LAS bf16x8*)(lds + PG8_SA(b, h) + aoff + m * 2048 + k * 1024); } while (0)
; #define PG8_MMA(ai, bj, At, Bt) do { __builtin_amdgcn_s_setprio(1); _Pragma("unroll") for (int m = 0; m < 4; ++m) _Pragma("unroll") for (int n = 0; n < 2; ++n) _Pragma("unroll") for (int k = 0; k < 2; ++k) \
;         acc[ai][bj][m][n] = __builtin_amdgcn_mfma_f32_16x16x32_bf16(Bt[n][k], At[m][k], acc[ai][bj][m][n], 0, 0, 0); __builtin_amdgcn_s_setprio(0); } while (0)
; #define PG8_WAIT_V(n) asm volatile("s_waitcnt vmcnt(" #n ")" ::: "memory")
; #define PG8_WAIT_L(n) asm volatile("s_waitcnt lgkmcnt(" #n ")" ::: "memory")
; #define PG8_BAR __builtin_amdgcn_s_barrier()
; #define PG8_SCHED __builtin_amdgcn_sched_barrier(0)
; template <class Epi, class Sched, bool ALIGN_EPI = false, bool SP2 = false>
; __device__ __forceinline__ void gemm_phase(PG8_LAS unsigned char* lds, const Gemm g, const Sched& S, const Epi& E) {
;     ...
;         for (int t = 0; t < nt; t += 2) {
;     ...
;             PG8_LDA(At, 1, 1); PG8_STAGE(PG8_SB(1, 0), b3, voffB); PG8_STAGE(PG8_SB(1, 1), b3 + hstep, voffB); PG8_STAGE(PG8_SA(1, 0), a3, voffA);
;             PG8_WAIT_V(8); PG8_WAIT_L(0); PG8_BAR; PG8_MMA(1, 0, At, B0); PG8_MMA(1, 1, At, B1); PG8_BAR; PG8_SCHED;
	s_add_i32 s56, s74, s39
	v_lshl_add_u64 v[200:201], v[200:201], 0, s[40:41]
	s_mov_b32 m0, s56
	ds_read_b128 v[192:195], v211 offset:49152
	ds_read_b128 v[196:199], v211 offset:50176
	ds_read_b128 v[212:215], v211 offset:51200
	ds_read_b128 v[216:219], v211 offset:52224
	ds_read_b128 v[220:223], v211 offset:53248
	ds_read_b128 v[224:227], v211 offset:54272
	ds_read_b128 v[228:231], v211 offset:55296
	ds_read_b128 v[232:235], v211 offset:56320
	global_load_lds_dwordx4 v[200:201], off
	v_lshl_add_u64 v[200:201], v[236:237], 0, s[40:41]
	s_add_i32 m0, s56, 0x2000
	s_add_i32 s56, s75, s39
	global_load_lds_dwordx4 v[200:201], off
	v_lshl_add_u64 v[200:201], v[238:239], 0, s[40:41]
	s_mov_b32 m0, s56
	s_nop 0
	global_load_lds_dwordx4 v[200:201], off
	v_lshl_add_u64 v[200:201], v[240:241], 0, s[40:41]
	s_add_i32 m0, s56, 0x2000
	s_nop 0
	global_load_lds_dwordx4 v[200:201], off
	v_lshl_add_u64 v[200:201], v[242:243], 0, s[40:41]
	s_mov_b32 m0, s66
	s_nop 0
	global_load_lds_dwordx4 v[200:201], off
	v_lshl_add_u64 v[200:201], v[244:245], 0, s[40:41]
	s_mov_b32 m0, s67
	s_nop 0
	global_load_lds_dwordx4 v[200:201], off
	s_waitcnt lgkmcnt(0)
	s_setprio 1
	s_barrier
	v_mfma_f32_16x16x32_bf16 v[60:63], v[134:137], v[192:195], v[60:63]
	v_mfma_f32_16x16x32_bf16 v[56:59], v[142:145], v[192:195], v[56:59]
	v_mfma_f32_16x16x32_bf16 v[44:47], v[134:137], v[212:215], v[44:47]
	v_mfma_f32_16x16x32_bf16 v[40:43], v[142:145], v[212:215], v[40:43]
	v_mfma_f32_16x16x32_bf16 v[28:31], v[134:137], v[220:223], v[28:31]
	v_mfma_f32_16x16x32_bf16 v[24:27], v[142:145], v[220:223], v[24:27]
	v_mfma_f32_16x16x32_bf16 v[12:15], v[134:137], v[228:231], v[12:15]
	v_mfma_f32_16x16x32_bf16 v[8:11], v[142:145], v[228:231], v[8:11]
	v_mfma_f32_16x16x32_bf16 v[60:63], v[138:141], v[196:199], v[60:63]
	v_mfma_f32_16x16x32_bf16 v[56:59], v[146:149], v[196:199], v[56:59]
	v_mfma_f32_16x16x32_bf16 v[44:47], v[138:141], v[216:219], v[44:47]
	v_mfma_f32_16x16x32_bf16 v[40:43], v[146:149], v[216:219], v[40:43]
	v_mfma_f32_16x16x32_bf16 v[28:31], v[138:141], v[224:227], v[28:31]
	v_mfma_f32_16x16x32_bf16 v[24:27], v[146:149], v[224:227], v[24:27]
	v_mfma_f32_16x16x32_bf16 v[12:15], v[138:141], v[232:235], v[12:15]
	v_mfma_f32_16x16x32_bf16 v[8:11], v[146:149], v[232:235], v[8:11]
	v_mfma_f32_16x16x32_bf16 v[52:55], v[150:153], v[192:195], v[52:55]
	v_mfma_f32_16x16x32_bf16 v[48:51], v[184:187], v[192:195], v[48:51]
	v_mfma_f32_16x16x32_bf16 v[36:39], v[150:153], v[212:215], v[36:39]
	v_mfma_f32_16x16x32_bf16 v[32:35], v[184:187], v[212:215], v[32:35]
	v_mfma_f32_16x16x32_bf16 v[20:23], v[150:153], v[220:223], v[20:23]
	v_mfma_f32_16x16x32_bf16 v[16:19], v[184:187], v[220:223], v[16:19]
	v_mfma_f32_16x16x32_bf16 v[4:7], v[150:153], v[228:231], v[4:7]
	v_mfma_f32_16x16x32_bf16 v[0:3], v[184:187], v[228:231], v[0:3]
	v_mfma_f32_16x16x32_bf16 v[52:55], v[154:157], v[196:199], v[52:55]
	v_mfma_f32_16x16x32_bf16 v[48:51], v[188:191], v[196:199], v[48:51]
	v_mfma_f32_16x16x32_bf16 v[36:39], v[154:157], v[216:219], v[36:39]
	v_mfma_f32_16x16x32_bf16 v[32:35], v[188:191], v[216:219], v[32:35]
	v_mfma_f32_16x16x32_bf16 v[20:23], v[154:157], v[224:227], v[20:23]
	v_mfma_f32_16x16x32_bf16 v[16:19], v[188:191], v[224:227], v[16:19]
	v_mfma_f32_16x16x32_bf16 v[4:7], v[154:157], v[232:235], v[4:7]
	v_mfma_f32_16x16x32_bf16 v[0:3], v[188:191], v[232:235], v[0:3]
	s_waitcnt vmcnt(8)
	s_setprio 0
	s_barrier
	s_add_u32 s54, s54, 0x100
	s_addc_u32 s55, s55, 0
	s_cmp_ge_u32 s73, s63
	s_mov_b32 s56, s73
	s_cbranch_scc1 .LBB0_386
